# code placement: all ten GEMM K-loop heads aligned to 64 B (p2align 6) on top of v_early1
# speedup vs baseline: 1.0059x; 1.0011x over previous
.LBB0_169:
	s_ashr_i32 s39, s38, 31
	s_lshl_b64 s[40:41], s[38:39], 21
	s_add_u32 s40, s34, s40
	s_addc_u32 s41, s35, s41
	s_and_b64 s[42:43], s[0:1], exec
	s_cselect_b32 s39, s41, s3
	s_cselect_b32 s82, s40, s2
	s_ashr_i32 s15, s14, 31
	s_lshl_b64 s[42:43], s[14:15], 21
	v_readlane_b32 s15, v253, 0
	s_add_u32 s42, s15, s42
	v_readlane_b32 s15, v253, 1
	s_addc_u32 s43, s15, s43
	s_and_b64 s[52:53], s[0:1], exec
	s_cselect_b32 s15, s43, s49
	s_cselect_b32 s83, s42, s48
	s_add_u32 s52, s2, 0x18000
	s_addc_u32 s53, s3, 0
	s_waitcnt lgkmcnt(0)
	s_add_u32 s54, s48, 0x18000
	s_addc_u32 s55, s49, 0
	s_barrier
	s_setprio 1
	s_waitcnt lgkmcnt(7)
	v_mfma_f32_16x16x32_bf16 v[112:115], v[16:19], v[104:107], 0
	s_waitcnt lgkmcnt(6)
	v_mfma_f32_16x16x32_bf16 v[152:155], v[20:23], v[108:111], v[112:115]
	v_mfma_f32_16x16x32_bf16 v[112:115], v[24:27], v[104:107], 0
	v_mfma_f32_16x16x32_bf16 v[156:159], v[28:31], v[108:111], v[112:115]
	s_waitcnt lgkmcnt(5)
	v_mfma_f32_16x16x32_bf16 v[112:115], v[16:19], v[96:99], 0
	s_waitcnt lgkmcnt(4)
	v_mfma_f32_16x16x32_bf16 v[160:163], v[20:23], v[100:103], v[112:115]
	v_mfma_f32_16x16x32_bf16 v[112:115], v[24:27], v[96:99], 0
	v_mfma_f32_16x16x32_bf16 v[172:175], v[28:31], v[100:103], v[112:115]
	s_waitcnt lgkmcnt(3)
	v_mfma_f32_16x16x32_bf16 v[112:115], v[16:19], v[80:83], 0
	s_waitcnt lgkmcnt(1)
	v_mfma_f32_16x16x32_bf16 v[16:19], v[16:19], v[60:63], 0
	v_mfma_f32_16x16x32_bf16 v[176:179], v[20:23], v[88:91], v[112:115]
	v_mfma_f32_16x16x32_bf16 v[112:115], v[24:27], v[80:83], 0
	s_waitcnt lgkmcnt(0)
	v_mfma_f32_16x16x32_bf16 v[20:23], v[20:23], v[72:75], v[16:19]
	v_mfma_f32_16x16x32_bf16 v[16:19], v[24:27], v[60:63], 0
	v_mfma_f32_16x16x32_bf16 v[180:183], v[28:31], v[88:91], v[112:115]
	v_mfma_f32_16x16x32_bf16 v[28:31], v[28:31], v[72:75], v[16:19]
	s_setprio 0
	s_setprio 1
	v_mfma_f32_16x16x32_bf16 v[16:19], v[0:3], v[104:107], 0
	v_mfma_f32_16x16x32_bf16 v[184:187], v[4:7], v[108:111], v[16:19]
	v_mfma_f32_16x16x32_bf16 v[16:19], v[8:11], v[104:107], 0
	v_mfma_f32_16x16x32_bf16 v[188:191], v[12:15], v[108:111], v[16:19]
	v_mfma_f32_16x16x32_bf16 v[16:19], v[0:3], v[96:99], 0
	v_mfma_f32_16x16x32_bf16 v[192:195], v[4:7], v[100:103], v[16:19]
	v_mfma_f32_16x16x32_bf16 v[16:19], v[8:11], v[96:99], 0
	v_mfma_f32_16x16x32_bf16 v[196:199], v[12:15], v[100:103], v[16:19]
	v_mfma_f32_16x16x32_bf16 v[16:19], v[0:3], v[80:83], 0
	v_mfma_f32_16x16x32_bf16 v[0:3], v[0:3], v[60:63], 0
	v_mfma_f32_16x16x32_bf16 v[200:203], v[4:7], v[88:91], v[16:19]
	v_mfma_f32_16x16x32_bf16 v[16:19], v[8:11], v[80:83], 0
	v_mfma_f32_16x16x32_bf16 v[4:7], v[4:7], v[72:75], v[0:3]
	v_mfma_f32_16x16x32_bf16 v[0:3], v[8:11], v[60:63], 0
	v_mfma_f32_16x16x32_bf16 v[204:207], v[12:15], v[88:91], v[16:19]
	v_mfma_f32_16x16x32_bf16 v[12:15], v[12:15], v[72:75], v[0:3]
	s_setprio 0
	s_barrier
	v_add_u32_e32 v148, 0x18000, v167
	v_add_u32_e32 v150, 0x1c000, v167
	s_nop 1
	ds_read_b128 v[0:3], v148
	ds_read_b128 v[8:11], v148 offset:1024
	ds_read_b128 v[208:211], v148 offset:2048
	ds_read_b128 v[212:215], v148 offset:3072
	ds_read_b128 v[216:219], v150
	ds_read_b128 v[220:223], v150 offset:1024
	ds_read_b128 v[224:227], v150 offset:2048
	ds_read_b128 v[228:231], v150 offset:3072
	ds_read_b128 v[16:19], v170 offset:32768
	ds_read_b128 v[24:27], v170 offset:33792
	ds_read_b128 v[108:111], v170 offset:34816
	ds_read_b128 v[232:235], v170 offset:35840
	ds_read_b128 v[236:239], v170 offset:36864
	ds_read_b128 v[240:243], v170 offset:37888
	ds_read_b128 v[244:247], v170 offset:38912
	ds_read_b128 v[248:251], v170 offset:39936
	s_add_u32 s80, s2, 0x14000
	s_addc_u32 s81, s3, 0
	s_mov_b32 m0, s61
	s_nop 0
	global_load_lds_dwordx4 v166, s[80:81]
	s_add_u32 s80, s2, 0x16000
	s_addc_u32 s81, s3, 0
	s_mov_b32 m0, s62
	s_nop 0
	global_load_lds_dwordx4 v166, s[80:81]
	s_waitcnt vmcnt(8)
	s_waitcnt lgkmcnt(0)
	s_barrier
	s_setprio 1
	s_waitcnt lgkmcnt(7)
	v_mfma_f32_16x16x32_bf16 v[32:35], v[0:3], v[16:19], v[32:35]
	s_waitcnt lgkmcnt(6)
	v_mfma_f32_16x16x32_bf16 v[112:115], v[8:11], v[24:27], v[32:35]
	v_mfma_f32_16x16x32_bf16 v[32:35], v[208:211], v[16:19], v[36:39]
	v_mfma_f32_16x16x32_bf16 v[120:123], v[212:215], v[24:27], v[32:35]
	s_waitcnt lgkmcnt(5)
	v_mfma_f32_16x16x32_bf16 v[32:35], v[0:3], v[108:111], v[40:43]
	s_waitcnt lgkmcnt(4)
	v_mfma_f32_16x16x32_bf16 v[96:99], v[8:11], v[232:235], v[32:35]
	v_mfma_f32_16x16x32_bf16 v[32:35], v[208:211], v[108:111], v[44:47]
	v_mfma_f32_16x16x32_bf16 v[104:107], v[212:215], v[232:235], v[32:35]
	s_waitcnt lgkmcnt(3)
	v_mfma_f32_16x16x32_bf16 v[32:35], v[0:3], v[236:239], v[48:51]
	s_waitcnt lgkmcnt(2)
	v_mfma_f32_16x16x32_bf16 v[80:83], v[8:11], v[240:243], v[32:35]
	v_mfma_f32_16x16x32_bf16 v[32:35], v[208:211], v[236:239], v[52:55]
	v_mfma_f32_16x16x32_bf16 v[88:91], v[212:215], v[240:243], v[32:35]
	s_waitcnt lgkmcnt(1)
	v_mfma_f32_16x16x32_bf16 v[32:35], v[0:3], v[244:247], v[56:59]
	s_waitcnt lgkmcnt(0)
	v_mfma_f32_16x16x32_bf16 v[60:63], v[8:11], v[248:251], v[32:35]
	v_mfma_f32_16x16x32_bf16 v[32:35], v[208:211], v[244:247], v[64:67]
	v_mfma_f32_16x16x32_bf16 v[72:75], v[212:215], v[248:251], v[32:35]
	s_setprio 0
	s_setprio 1
	v_mfma_f32_16x16x32_bf16 v[32:35], v[216:219], v[16:19], v[68:71]
	v_mfma_f32_16x16x32_bf16 v[16:19], v[224:227], v[16:19], v[76:79]
	v_mfma_f32_16x16x32_bf16 v[124:127], v[228:231], v[24:27], v[16:19]
	v_mfma_f32_16x16x32_bf16 v[16:19], v[216:219], v[108:111], v[84:87]
	v_mfma_f32_16x16x32_bf16 v[100:103], v[220:223], v[232:235], v[16:19]
	v_mfma_f32_16x16x32_bf16 v[16:19], v[224:227], v[108:111], v[92:95]
	v_mfma_f32_16x16x32_bf16 v[108:111], v[228:231], v[232:235], v[16:19]
	v_mfma_f32_16x16x32_bf16 v[16:19], v[216:219], v[236:239], v[128:131]
	v_mfma_f32_16x16x32_bf16 v[84:87], v[220:223], v[240:243], v[16:19]
	v_mfma_f32_16x16x32_bf16 v[16:19], v[224:227], v[236:239], v[132:135]
	v_mfma_f32_16x16x32_bf16 v[92:95], v[228:231], v[240:243], v[16:19]
	v_mfma_f32_16x16x32_bf16 v[16:19], v[216:219], v[244:247], v[136:139]
	v_mfma_f32_16x16x32_bf16 v[68:71], v[220:223], v[248:251], v[16:19]
	v_mfma_f32_16x16x32_bf16 v[16:19], v[224:227], v[244:247], v[140:143]
	v_mfma_f32_16x16x32_bf16 v[116:119], v[220:223], v[24:27], v[32:35]
	v_mfma_f32_16x16x32_bf16 v[76:79], v[228:231], v[248:251], v[16:19]
	s_setprio 0
	s_barrier
	ds_read_b128 v[36:39], v170 offset:49152
	ds_read_b128 v[44:47], v170 offset:50176
	ds_read_b128 v[128:131], v170 offset:51200
	ds_read_b128 v[132:135], v170 offset:52224
	ds_read_b128 v[136:139], v170 offset:53248
	ds_read_b128 v[140:143], v170 offset:54272
	ds_read_b128 v[232:235], v170 offset:55296
	ds_read_b128 v[236:239], v170 offset:56320
	s_mov_b32 m0, s66
	s_nop 0
	global_load_lds_dwordx4 v166, s[54:55]
	s_add_u32 s54, s48, 0x1a000
	s_addc_u32 s55, s49, 0
	s_mov_b32 m0, s67
	s_nop 0
	global_load_lds_dwordx4 v166, s[54:55]
	s_add_u32 s54, s48, 0x1c000
	s_addc_u32 s55, s49, 0
	s_mov_b32 m0, s70
	s_nop 0
	global_load_lds_dwordx4 v166, s[54:55]
	s_add_u32 s54, s48, 0x1e000
	s_addc_u32 s55, s49, 0
	s_mov_b32 m0, s71
	s_nop 0
	global_load_lds_dwordx4 v166, s[54:55]
	s_nop 0
	s_mov_b32 m0, s68
	s_nop 0
	global_load_lds_dwordx4 v166, s[52:53]
	s_add_u32 s52, s2, 0x1a000
	s_addc_u32 s53, s3, 0
	s_mov_b32 m0, s69
	s_nop 0
	global_load_lds_dwordx4 v166, s[52:53]
	s_waitcnt vmcnt(8)
	s_waitcnt lgkmcnt(0)
	s_barrier
	s_setprio 1
	s_waitcnt lgkmcnt(7)
	v_mfma_f32_16x16x32_bf16 v[16:19], v[0:3], v[36:39], v[152:155]
	s_waitcnt lgkmcnt(6)
	v_mfma_f32_16x16x32_bf16 v[48:51], v[8:11], v[44:47], v[16:19]
	v_mfma_f32_16x16x32_bf16 v[16:19], v[208:211], v[36:39], v[156:159]
	v_mfma_f32_16x16x32_bf16 v[56:59], v[212:215], v[44:47], v[16:19]
	s_waitcnt lgkmcnt(5)
	v_mfma_f32_16x16x32_bf16 v[16:19], v[0:3], v[128:131], v[160:163]
	s_waitcnt lgkmcnt(4)
	v_mfma_f32_16x16x32_bf16 v[32:35], v[8:11], v[132:135], v[16:19]
	v_mfma_f32_16x16x32_bf16 v[16:19], v[208:211], v[128:131], v[172:175]
	v_mfma_f32_16x16x32_bf16 v[40:43], v[212:215], v[132:135], v[16:19]
	s_waitcnt lgkmcnt(3)
	v_mfma_f32_16x16x32_bf16 v[16:19], v[0:3], v[136:139], v[176:179]
	s_waitcnt lgkmcnt(1)
	v_mfma_f32_16x16x32_bf16 v[0:3], v[0:3], v[232:235], v[20:23]
	v_mfma_f32_16x16x32_bf16 v[16:19], v[8:11], v[140:143], v[16:19]
	v_mfma_f32_16x16x32_bf16 v[24:27], v[208:211], v[136:139], v[180:183]
	s_waitcnt lgkmcnt(0)
	v_mfma_f32_16x16x32_bf16 v[0:3], v[8:11], v[236:239], v[0:3]
	v_mfma_f32_16x16x32_bf16 v[8:11], v[208:211], v[232:235], v[28:31]
	v_mfma_f32_16x16x32_bf16 v[24:27], v[212:215], v[140:143], v[24:27]
	v_mfma_f32_16x16x32_bf16 v[8:11], v[212:215], v[236:239], v[8:11]
	s_setprio 0
	s_setprio 1
	v_mfma_f32_16x16x32_bf16 v[20:23], v[216:219], v[36:39], v[184:187]
	v_mfma_f32_16x16x32_bf16 v[52:55], v[220:223], v[44:47], v[20:23]
	v_mfma_f32_16x16x32_bf16 v[20:23], v[224:227], v[36:39], v[188:191]
	v_mfma_f32_16x16x32_bf16 v[64:67], v[228:231], v[44:47], v[20:23]
	v_mfma_f32_16x16x32_bf16 v[20:23], v[216:219], v[128:131], v[192:195]
	v_mfma_f32_16x16x32_bf16 v[36:39], v[220:223], v[132:135], v[20:23]
	v_mfma_f32_16x16x32_bf16 v[20:23], v[224:227], v[128:131], v[196:199]
	v_mfma_f32_16x16x32_bf16 v[44:47], v[228:231], v[132:135], v[20:23]
	v_mfma_f32_16x16x32_bf16 v[20:23], v[216:219], v[136:139], v[200:203]
	v_mfma_f32_16x16x32_bf16 v[28:31], v[224:227], v[136:139], v[204:207]
	v_mfma_f32_16x16x32_bf16 v[4:7], v[216:219], v[232:235], v[4:7]
	v_mfma_f32_16x16x32_bf16 v[12:15], v[224:227], v[232:235], v[12:15]
	v_mfma_f32_16x16x32_bf16 v[20:23], v[220:223], v[140:143], v[20:23]
	v_mfma_f32_16x16x32_bf16 v[28:31], v[228:231], v[140:143], v[28:31]
	v_mfma_f32_16x16x32_bf16 v[4:7], v[220:223], v[236:239], v[4:7]
	v_mfma_f32_16x16x32_bf16 v[12:15], v[228:231], v[236:239], v[12:15]
	s_setprio 0
	s_barrier
	s_add_u32 s52, s2, 0x10000
	s_addc_u32 s53, s3, 0
	s_add_u32 s54, s48, 0x20000
	s_addc_u32 s55, s49, 0
	s_mov_b32 s88, 0
	.p2align	6

.LBB0_325:
	s_add_u32 s2, s42, 0x18000
	s_waitcnt lgkmcnt(0)
	s_addc_u32 s3, s43, 0
	s_add_u32 s44, s40, 0x18000
	s_addc_u32 s45, s41, 0
	s_barrier
	s_setprio 1
	s_waitcnt lgkmcnt(7)
	v_mfma_f32_16x16x32_bf16 v[128:131], v[16:19], v[120:123], 0
	s_waitcnt lgkmcnt(6)
	v_mfma_f32_16x16x32_bf16 v[138:141], v[20:23], v[124:127], v[128:131]
	v_mfma_f32_16x16x32_bf16 v[128:131], v[24:27], v[120:123], 0
	v_mfma_f32_16x16x32_bf16 v[152:155], v[28:31], v[124:127], v[128:131]
	s_waitcnt lgkmcnt(5)
	v_mfma_f32_16x16x32_bf16 v[128:131], v[16:19], v[104:107], 0
	s_waitcnt lgkmcnt(4)
	v_mfma_f32_16x16x32_bf16 v[164:167], v[20:23], v[108:111], v[128:131]
	v_mfma_f32_16x16x32_bf16 v[128:131], v[24:27], v[104:107], 0
	v_mfma_f32_16x16x32_bf16 v[168:171], v[28:31], v[108:111], v[128:131]
	s_waitcnt lgkmcnt(3)
	v_mfma_f32_16x16x32_bf16 v[128:131], v[16:19], v[96:99], 0
	s_waitcnt lgkmcnt(1)
	v_mfma_f32_16x16x32_bf16 v[16:19], v[16:19], v[80:83], 0
	v_mfma_f32_16x16x32_bf16 v[172:175], v[20:23], v[100:103], v[128:131]
	s_waitcnt lgkmcnt(0)
	v_mfma_f32_16x16x32_bf16 v[16:19], v[20:23], v[84:87], v[16:19]
	v_mfma_f32_16x16x32_bf16 v[20:23], v[24:27], v[80:83], 0
	v_mfma_f32_16x16x32_bf16 v[128:131], v[24:27], v[96:99], 0
	v_mfma_f32_16x16x32_bf16 v[20:23], v[28:31], v[84:87], v[20:23]
	v_mfma_f32_16x16x32_bf16 v[176:179], v[28:31], v[100:103], v[128:131]
	s_setprio 0
	s_setprio 1
	v_mfma_f32_16x16x32_bf16 v[24:27], v[0:3], v[120:123], 0
	v_mfma_f32_16x16x32_bf16 v[180:183], v[4:7], v[124:127], v[24:27]
	v_mfma_f32_16x16x32_bf16 v[24:27], v[8:11], v[120:123], 0
	v_mfma_f32_16x16x32_bf16 v[184:187], v[12:15], v[124:127], v[24:27]
	v_mfma_f32_16x16x32_bf16 v[24:27], v[0:3], v[104:107], 0
	v_mfma_f32_16x16x32_bf16 v[192:195], v[4:7], v[108:111], v[24:27]
	v_mfma_f32_16x16x32_bf16 v[24:27], v[8:11], v[104:107], 0
	v_mfma_f32_16x16x32_bf16 v[196:199], v[12:15], v[108:111], v[24:27]
	v_mfma_f32_16x16x32_bf16 v[24:27], v[0:3], v[96:99], 0
	v_mfma_f32_16x16x32_bf16 v[0:3], v[0:3], v[80:83], 0
	v_mfma_f32_16x16x32_bf16 v[200:203], v[4:7], v[100:103], v[24:27]
	v_mfma_f32_16x16x32_bf16 v[24:27], v[8:11], v[96:99], 0
	v_mfma_f32_16x16x32_bf16 v[0:3], v[4:7], v[84:87], v[0:3]
	v_mfma_f32_16x16x32_bf16 v[4:7], v[8:11], v[80:83], 0
	v_mfma_f32_16x16x32_bf16 v[204:207], v[12:15], v[100:103], v[24:27]
	v_mfma_f32_16x16x32_bf16 v[216:219], v[12:15], v[84:87], v[4:7]
	s_setprio 0
	s_barrier
	v_add_u32_e32 v136, 0x18000, v211
	v_add_u32_e32 v137, 0x1c000, v211
	s_nop 1
	ds_read_b128 v[4:7], v136
	ds_read_b128 v[8:11], v136 offset:1024
	ds_read_b128 v[220:223], v136 offset:2048
	ds_read_b128 v[224:227], v136 offset:3072
	ds_read_b128 v[228:231], v137
	ds_read_b128 v[232:235], v137 offset:1024
	ds_read_b128 v[236:239], v137 offset:2048
	ds_read_b128 v[240:243], v137 offset:3072
	ds_read_b128 v[12:15], v214 offset:32768
	ds_read_b128 v[24:27], v214 offset:33792
	ds_read_b128 v[28:31], v214 offset:34816
	ds_read_b128 v[96:99], v214 offset:35840
	ds_read_b128 v[244:247], v214 offset:36864
	ds_read_b128 v[248:251], v214 offset:37888
	ds_read_b128 v[188:191], v214 offset:38912
	ds_read_b128 v[32:35], v214 offset:39936
	s_add_u32 s76, s42, 0x14000
	s_addc_u32 s77, s43, 0
	s_mov_b32 m0, s54
	s_nop 0
	global_load_lds_dwordx4 v210, s[76:77]
	s_add_u32 s76, s42, 0x16000
	s_addc_u32 s77, s43, 0
	s_mov_b32 m0, s55
	s_nop 0
	global_load_lds_dwordx4 v210, s[76:77]
	s_waitcnt vmcnt(8)
	s_waitcnt lgkmcnt(0)
	s_barrier
	s_setprio 1
	s_waitcnt lgkmcnt(7)
	v_mfma_f32_16x16x32_bf16 v[36:39], v[220:223], v[12:15], v[36:39]
	s_waitcnt lgkmcnt(6)
	v_mfma_f32_16x16x32_bf16 v[156:159], v[224:227], v[24:27], v[36:39]
	s_waitcnt lgkmcnt(5)
	v_mfma_f32_16x16x32_bf16 v[36:39], v[4:7], v[28:31], v[40:43]
	v_mfma_f32_16x16x32_bf16 v[80:83], v[4:7], v[12:15], v[132:135]
	s_waitcnt lgkmcnt(4)
	v_mfma_f32_16x16x32_bf16 v[132:135], v[8:11], v[96:99], v[36:39]
	v_mfma_f32_16x16x32_bf16 v[36:39], v[220:223], v[28:31], v[44:47]
	v_mfma_f32_16x16x32_bf16 v[128:131], v[224:227], v[96:99], v[36:39]
	s_waitcnt lgkmcnt(3)
	v_mfma_f32_16x16x32_bf16 v[36:39], v[4:7], v[244:247], v[48:51]
	s_waitcnt lgkmcnt(2)
	v_mfma_f32_16x16x32_bf16 v[108:111], v[8:11], v[248:251], v[36:39]
	v_mfma_f32_16x16x32_bf16 v[36:39], v[220:223], v[244:247], v[52:55]
	v_mfma_f32_16x16x32_bf16 v[104:107], v[224:227], v[248:251], v[36:39]
	s_waitcnt lgkmcnt(1)
	v_mfma_f32_16x16x32_bf16 v[36:39], v[4:7], v[188:191], v[56:59]
	s_waitcnt lgkmcnt(0)
	v_mfma_f32_16x16x32_bf16 v[84:87], v[8:11], v[32:35], v[36:39]
	v_mfma_f32_16x16x32_bf16 v[36:39], v[220:223], v[188:191], v[60:63]
	v_mfma_f32_16x16x32_bf16 v[160:163], v[8:11], v[24:27], v[80:83]
	v_mfma_f32_16x16x32_bf16 v[80:83], v[224:227], v[32:35], v[36:39]
	s_setprio 0
	s_setprio 1
	v_mfma_f32_16x16x32_bf16 v[36:39], v[228:231], v[12:15], v[64:67]
	v_mfma_f32_16x16x32_bf16 v[12:15], v[236:239], v[12:15], v[68:71]
	v_mfma_f32_16x16x32_bf16 v[144:147], v[240:243], v[24:27], v[12:15]
	v_mfma_f32_16x16x32_bf16 v[12:15], v[228:231], v[28:31], v[72:75]
	v_mfma_f32_16x16x32_bf16 v[124:127], v[232:235], v[96:99], v[12:15]
	v_mfma_f32_16x16x32_bf16 v[12:15], v[236:239], v[28:31], v[76:79]
	v_mfma_f32_16x16x32_bf16 v[120:123], v[240:243], v[96:99], v[12:15]
	v_mfma_f32_16x16x32_bf16 v[12:15], v[228:231], v[244:247], v[88:91]
	v_mfma_f32_16x16x32_bf16 v[100:103], v[232:235], v[248:251], v[12:15]
	v_mfma_f32_16x16x32_bf16 v[12:15], v[236:239], v[244:247], v[92:95]
	v_mfma_f32_16x16x32_bf16 v[96:99], v[240:243], v[248:251], v[12:15]
	v_mfma_f32_16x16x32_bf16 v[12:15], v[228:231], v[188:191], v[112:115]
	v_mfma_f32_16x16x32_bf16 v[76:79], v[232:235], v[32:35], v[12:15]
	v_mfma_f32_16x16x32_bf16 v[12:15], v[236:239], v[188:191], v[116:119]
	v_mfma_f32_16x16x32_bf16 v[148:151], v[232:235], v[24:27], v[36:39]
	v_mfma_f32_16x16x32_bf16 v[72:75], v[240:243], v[32:35], v[12:15]
	s_setprio 0
	s_barrier
	ds_read_b128 v[32:35], v214 offset:49152
	ds_read_b128 v[36:39], v214 offset:50176
	ds_read_b128 v[60:63], v214 offset:51200
	ds_read_b128 v[68:71], v214 offset:52224
	ds_read_b128 v[88:91], v214 offset:53248
	ds_read_b128 v[92:95], v214 offset:54272
	ds_read_b128 v[112:115], v214 offset:55296
	ds_read_b128 v[116:119], v214 offset:56320
	s_mov_b32 m0, s59
	s_nop 0
	global_load_lds_dwordx4 v210, s[44:45]
	s_add_u32 s44, s40, 0x1a000
	s_addc_u32 s45, s41, 0
	s_mov_b32 m0, s60
	s_nop 0
	global_load_lds_dwordx4 v210, s[44:45]
	s_add_u32 s44, s40, 0x1c000
	s_addc_u32 s45, s41, 0
	s_mov_b32 m0, s63
	s_nop 0
	global_load_lds_dwordx4 v210, s[44:45]
	s_add_u32 s44, s40, 0x1e000
	s_addc_u32 s45, s41, 0
	s_mov_b32 m0, s64
	s_nop 0
	global_load_lds_dwordx4 v210, s[44:45]
	s_nop 0
	s_mov_b32 m0, s61
	s_nop 0
	global_load_lds_dwordx4 v210, s[2:3]
	s_add_u32 s2, s42, 0x1a000
	s_addc_u32 s3, s43, 0
	s_mov_b32 m0, s62
	s_nop 0
	global_load_lds_dwordx4 v210, s[2:3]
	s_waitcnt vmcnt(8)
	s_waitcnt lgkmcnt(0)
	s_barrier
	s_setprio 1
	s_waitcnt lgkmcnt(7)
	v_mfma_f32_16x16x32_bf16 v[12:15], v[4:7], v[32:35], v[138:141]
	s_waitcnt lgkmcnt(6)
	v_mfma_f32_16x16x32_bf16 v[64:67], v[8:11], v[36:39], v[12:15]
	v_mfma_f32_16x16x32_bf16 v[12:15], v[220:223], v[32:35], v[152:155]
	v_mfma_f32_16x16x32_bf16 v[56:59], v[224:227], v[36:39], v[12:15]
	s_waitcnt lgkmcnt(5)
	v_mfma_f32_16x16x32_bf16 v[12:15], v[4:7], v[60:63], v[164:167]
	s_waitcnt lgkmcnt(4)
	v_mfma_f32_16x16x32_bf16 v[44:47], v[8:11], v[68:71], v[12:15]
	v_mfma_f32_16x16x32_bf16 v[12:15], v[220:223], v[60:63], v[168:171]
	v_mfma_f32_16x16x32_bf16 v[40:43], v[224:227], v[68:71], v[12:15]
	s_waitcnt lgkmcnt(3)
	v_mfma_f32_16x16x32_bf16 v[12:15], v[4:7], v[88:91], v[172:175]
	s_waitcnt lgkmcnt(2)
	v_mfma_f32_16x16x32_bf16 v[28:31], v[8:11], v[92:95], v[12:15]
	v_mfma_f32_16x16x32_bf16 v[12:15], v[220:223], v[88:91], v[176:179]
	s_waitcnt lgkmcnt(1)
	v_mfma_f32_16x16x32_bf16 v[4:7], v[4:7], v[112:115], v[16:19]
	v_mfma_f32_16x16x32_bf16 v[24:27], v[224:227], v[92:95], v[12:15]
	s_waitcnt lgkmcnt(0)
	v_mfma_f32_16x16x32_bf16 v[12:15], v[8:11], v[116:119], v[4:7]
	v_mfma_f32_16x16x32_bf16 v[4:7], v[220:223], v[112:115], v[20:23]
	v_mfma_f32_16x16x32_bf16 v[8:11], v[224:227], v[116:119], v[4:7]
	s_setprio 0
	s_setprio 1
	v_mfma_f32_16x16x32_bf16 v[4:7], v[228:231], v[32:35], v[180:183]
	v_mfma_f32_16x16x32_bf16 v[52:55], v[232:235], v[36:39], v[4:7]
	v_mfma_f32_16x16x32_bf16 v[4:7], v[236:239], v[32:35], v[184:187]
	v_mfma_f32_16x16x32_bf16 v[48:51], v[240:243], v[36:39], v[4:7]
	v_mfma_f32_16x16x32_bf16 v[4:7], v[228:231], v[60:63], v[192:195]
	v_mfma_f32_16x16x32_bf16 v[36:39], v[232:235], v[68:71], v[4:7]
	v_mfma_f32_16x16x32_bf16 v[4:7], v[236:239], v[60:63], v[196:199]
	v_mfma_f32_16x16x32_bf16 v[32:35], v[240:243], v[68:71], v[4:7]
	v_mfma_f32_16x16x32_bf16 v[4:7], v[228:231], v[88:91], v[200:203]
	v_mfma_f32_16x16x32_bf16 v[20:23], v[232:235], v[92:95], v[4:7]
	v_mfma_f32_16x16x32_bf16 v[4:7], v[236:239], v[88:91], v[204:207]
	v_mfma_f32_16x16x32_bf16 v[0:3], v[228:231], v[112:115], v[0:3]
	v_mfma_f32_16x16x32_bf16 v[16:19], v[240:243], v[92:95], v[4:7]
	v_mfma_f32_16x16x32_bf16 v[4:7], v[232:235], v[116:119], v[0:3]
	v_mfma_f32_16x16x32_bf16 v[0:3], v[236:239], v[112:115], v[216:219]
	v_mfma_f32_16x16x32_bf16 v[0:3], v[240:243], v[116:119], v[0:3]
	s_setprio 0
	s_barrier
	s_add_u32 s76, s42, 0x20000
	s_addc_u32 s77, s43, 0
	s_add_u32 s78, s40, 0x20000
	s_addc_u32 s79, s41, 0
	s_mov_b32 s80, 0
	.p2align	6

.LBB0_424:
	s_ashr_i32 s47, s46, 31
	s_lshl_b64 s[2:3], s[46:47], 21
	s_add_u32 s8, s34, s2
	s_addc_u32 s9, s35, s3
	s_and_b64 s[2:3], s[0:1], exec
	s_cselect_b32 s5, s9, s49
	s_cselect_b32 s10, s8, s48
	s_ashr_i32 s45, s44, 31
	s_lshl_b64 s[2:3], s[44:45], 21
	v_readlane_b32 s50, v253, 8
	v_readlane_b32 s51, v253, 9
	s_add_u32 s92, s50, s2
	s_addc_u32 s93, s51, s3
	s_and_b64 s[2:3], s[0:1], exec
	s_cselect_b32 s45, s93, s81
	s_cselect_b32 s47, s92, s80
	s_add_u32 s2, s48, 0x18000
	s_addc_u32 s3, s49, 0
	s_waitcnt lgkmcnt(0)
	s_add_u32 s52, s80, 0x18000
	s_addc_u32 s53, s81, 0
	s_barrier
	s_setprio 1
	s_waitcnt lgkmcnt(7)
	v_mfma_f32_16x16x32_bf16 v[112:115], v[16:19], v[104:107], 0
	s_waitcnt lgkmcnt(6)
	v_mfma_f32_16x16x32_bf16 v[152:155], v[20:23], v[108:111], v[112:115]
	v_mfma_f32_16x16x32_bf16 v[112:115], v[24:27], v[104:107], 0
	v_mfma_f32_16x16x32_bf16 v[156:159], v[28:31], v[108:111], v[112:115]
	s_waitcnt lgkmcnt(5)
	v_mfma_f32_16x16x32_bf16 v[112:115], v[16:19], v[96:99], 0
	s_waitcnt lgkmcnt(4)
	v_mfma_f32_16x16x32_bf16 v[168:171], v[20:23], v[100:103], v[112:115]
	v_mfma_f32_16x16x32_bf16 v[112:115], v[24:27], v[96:99], 0
	v_mfma_f32_16x16x32_bf16 v[172:175], v[28:31], v[100:103], v[112:115]
	s_waitcnt lgkmcnt(3)
	v_mfma_f32_16x16x32_bf16 v[112:115], v[16:19], v[88:91], 0
	s_waitcnt lgkmcnt(1)
	v_mfma_f32_16x16x32_bf16 v[16:19], v[16:19], v[72:75], 0
	v_mfma_f32_16x16x32_bf16 v[176:179], v[20:23], v[92:95], v[112:115]
	s_waitcnt lgkmcnt(0)
	v_mfma_f32_16x16x32_bf16 v[16:19], v[20:23], v[76:79], v[16:19]
	v_mfma_f32_16x16x32_bf16 v[20:23], v[24:27], v[72:75], 0
	v_mfma_f32_16x16x32_bf16 v[112:115], v[24:27], v[88:91], 0
	v_mfma_f32_16x16x32_bf16 v[20:23], v[28:31], v[76:79], v[20:23]
	v_mfma_f32_16x16x32_bf16 v[180:183], v[28:31], v[92:95], v[112:115]
	s_setprio 0
	s_setprio 1
	v_mfma_f32_16x16x32_bf16 v[24:27], v[0:3], v[104:107], 0
	v_mfma_f32_16x16x32_bf16 v[184:187], v[4:7], v[108:111], v[24:27]
	v_mfma_f32_16x16x32_bf16 v[24:27], v[8:11], v[104:107], 0
	v_mfma_f32_16x16x32_bf16 v[188:191], v[12:15], v[108:111], v[24:27]
	v_mfma_f32_16x16x32_bf16 v[24:27], v[0:3], v[96:99], 0
	v_mfma_f32_16x16x32_bf16 v[192:195], v[4:7], v[100:103], v[24:27]
	v_mfma_f32_16x16x32_bf16 v[24:27], v[8:11], v[96:99], 0
	v_mfma_f32_16x16x32_bf16 v[196:199], v[12:15], v[100:103], v[24:27]
	v_mfma_f32_16x16x32_bf16 v[24:27], v[0:3], v[88:91], 0
	v_mfma_f32_16x16x32_bf16 v[0:3], v[0:3], v[72:75], 0
	v_mfma_f32_16x16x32_bf16 v[200:203], v[4:7], v[92:95], v[24:27]
	v_mfma_f32_16x16x32_bf16 v[24:27], v[8:11], v[88:91], 0
	v_mfma_f32_16x16x32_bf16 v[0:3], v[4:7], v[76:79], v[0:3]
	v_mfma_f32_16x16x32_bf16 v[4:7], v[8:11], v[72:75], 0
	v_mfma_f32_16x16x32_bf16 v[204:207], v[12:15], v[92:95], v[24:27]
	v_mfma_f32_16x16x32_bf16 v[208:211], v[12:15], v[76:79], v[4:7]
	s_setprio 0
	s_barrier
	v_add_u32_e32 v148, 0x18000, v161
	v_add_u32_e32 v150, 0x1c000, v161
	s_nop 1
	ds_read_b128 v[4:7], v148
	ds_read_b128 v[8:11], v148 offset:1024
	ds_read_b128 v[212:215], v148 offset:2048
	ds_read_b128 v[216:219], v148 offset:3072
	ds_read_b128 v[220:223], v150
	ds_read_b128 v[224:227], v150 offset:1024
	ds_read_b128 v[228:231], v150 offset:2048
	ds_read_b128 v[232:235], v150 offset:3072
	ds_read_b128 v[12:15], v164 offset:32768
	ds_read_b128 v[24:27], v164 offset:33792
	ds_read_b128 v[28:31], v164 offset:34816
	ds_read_b128 v[96:99], v164 offset:35840
	ds_read_b128 v[236:239], v164 offset:36864
	ds_read_b128 v[240:243], v164 offset:37888
	ds_read_b128 v[244:247], v164 offset:38912
	ds_read_b128 v[248:251], v164 offset:39936
	s_add_u32 s78, s48, 0x14000
	s_addc_u32 s79, s49, 0
	s_mov_b32 m0, s60
	s_nop 0
	global_load_lds_dwordx4 v160, s[78:79]
	s_add_u32 s78, s48, 0x16000
	s_addc_u32 s79, s49, 0
	s_mov_b32 m0, s61
	s_nop 0
	global_load_lds_dwordx4 v160, s[78:79]
	s_waitcnt vmcnt(8)
	s_waitcnt lgkmcnt(0)
	s_barrier
	s_setprio 1
	s_waitcnt lgkmcnt(7)
	v_mfma_f32_16x16x32_bf16 v[32:35], v[4:7], v[12:15], v[32:35]
	s_waitcnt lgkmcnt(6)
	v_mfma_f32_16x16x32_bf16 v[124:127], v[8:11], v[24:27], v[32:35]
	v_mfma_f32_16x16x32_bf16 v[32:35], v[212:215], v[12:15], v[36:39]
	v_mfma_f32_16x16x32_bf16 v[120:123], v[216:219], v[24:27], v[32:35]
	s_waitcnt lgkmcnt(5)
	v_mfma_f32_16x16x32_bf16 v[32:35], v[4:7], v[28:31], v[40:43]
	s_waitcnt lgkmcnt(4)
	v_mfma_f32_16x16x32_bf16 v[108:111], v[8:11], v[96:99], v[32:35]
	v_mfma_f32_16x16x32_bf16 v[32:35], v[212:215], v[28:31], v[44:47]
	v_mfma_f32_16x16x32_bf16 v[104:107], v[216:219], v[96:99], v[32:35]
	s_waitcnt lgkmcnt(3)
	v_mfma_f32_16x16x32_bf16 v[32:35], v[4:7], v[236:239], v[48:51]
	s_waitcnt lgkmcnt(2)
	v_mfma_f32_16x16x32_bf16 v[92:95], v[8:11], v[240:243], v[32:35]
	v_mfma_f32_16x16x32_bf16 v[32:35], v[212:215], v[236:239], v[52:55]
	v_mfma_f32_16x16x32_bf16 v[88:91], v[216:219], v[240:243], v[32:35]
	s_waitcnt lgkmcnt(1)
	v_mfma_f32_16x16x32_bf16 v[32:35], v[4:7], v[244:247], v[56:59]
	s_waitcnt lgkmcnt(0)
	v_mfma_f32_16x16x32_bf16 v[76:79], v[8:11], v[248:251], v[32:35]
	v_mfma_f32_16x16x32_bf16 v[32:35], v[212:215], v[244:247], v[60:63]
	v_mfma_f32_16x16x32_bf16 v[72:75], v[216:219], v[248:251], v[32:35]
	s_setprio 0
	s_setprio 1
	v_mfma_f32_16x16x32_bf16 v[32:35], v[220:223], v[12:15], v[64:67]
	v_mfma_f32_16x16x32_bf16 v[12:15], v[228:231], v[12:15], v[68:71]
	v_mfma_f32_16x16x32_bf16 v[112:115], v[232:235], v[24:27], v[12:15]
	v_mfma_f32_16x16x32_bf16 v[12:15], v[220:223], v[28:31], v[80:83]
	v_mfma_f32_16x16x32_bf16 v[100:103], v[224:227], v[96:99], v[12:15]
	v_mfma_f32_16x16x32_bf16 v[12:15], v[228:231], v[28:31], v[84:87]
	v_mfma_f32_16x16x32_bf16 v[96:99], v[232:235], v[96:99], v[12:15]
	v_mfma_f32_16x16x32_bf16 v[12:15], v[220:223], v[236:239], v[128:131]
	v_mfma_f32_16x16x32_bf16 v[84:87], v[224:227], v[240:243], v[12:15]
	v_mfma_f32_16x16x32_bf16 v[12:15], v[228:231], v[236:239], v[132:135]
	v_mfma_f32_16x16x32_bf16 v[80:83], v[232:235], v[240:243], v[12:15]
	v_mfma_f32_16x16x32_bf16 v[12:15], v[220:223], v[244:247], v[136:139]
	v_mfma_f32_16x16x32_bf16 v[68:71], v[224:227], v[248:251], v[12:15]
	v_mfma_f32_16x16x32_bf16 v[12:15], v[228:231], v[244:247], v[140:143]
	v_mfma_f32_16x16x32_bf16 v[116:119], v[224:227], v[24:27], v[32:35]
	v_mfma_f32_16x16x32_bf16 v[64:67], v[232:235], v[248:251], v[12:15]
	s_setprio 0
	s_barrier
	ds_read_b128 v[32:35], v164 offset:49152
	ds_read_b128 v[36:39], v164 offset:50176
	ds_read_b128 v[128:131], v164 offset:51200
	ds_read_b128 v[132:135], v164 offset:52224
	ds_read_b128 v[136:139], v164 offset:53248
	ds_read_b128 v[140:143], v164 offset:54272
	ds_read_b128 v[236:239], v164 offset:55296
	ds_read_b128 v[240:243], v164 offset:56320
	s_mov_b32 m0, s64
	s_nop 0
	global_load_lds_dwordx4 v160, s[52:53]
	s_add_u32 s52, s80, 0x1a000
	s_addc_u32 s53, s81, 0
	s_mov_b32 m0, s65
	s_nop 0
	global_load_lds_dwordx4 v160, s[52:53]
	s_add_u32 s52, s80, 0x1c000
	s_addc_u32 s53, s81, 0
	s_mov_b32 m0, s68
	s_nop 0
	global_load_lds_dwordx4 v160, s[52:53]
	s_add_u32 s52, s80, 0x1e000
	s_addc_u32 s53, s81, 0
	s_mov_b32 m0, s69
	s_nop 0
	global_load_lds_dwordx4 v160, s[52:53]
	s_nop 0
	s_mov_b32 m0, s66
	s_nop 0
	global_load_lds_dwordx4 v160, s[2:3]
	s_add_u32 s2, s48, 0x1a000
	s_addc_u32 s3, s49, 0
	s_mov_b32 m0, s67
	s_nop 0
	global_load_lds_dwordx4 v160, s[2:3]
	s_waitcnt vmcnt(8)
	s_waitcnt lgkmcnt(0)
	s_barrier
	s_setprio 1
	s_waitcnt lgkmcnt(7)
	v_mfma_f32_16x16x32_bf16 v[12:15], v[4:7], v[32:35], v[152:155]
	s_waitcnt lgkmcnt(6)
	v_mfma_f32_16x16x32_bf16 v[60:63], v[8:11], v[36:39], v[12:15]
	v_mfma_f32_16x16x32_bf16 v[12:15], v[212:215], v[32:35], v[156:159]
	v_mfma_f32_16x16x32_bf16 v[56:59], v[216:219], v[36:39], v[12:15]
	s_waitcnt lgkmcnt(5)
	v_mfma_f32_16x16x32_bf16 v[12:15], v[4:7], v[128:131], v[168:171]
	s_waitcnt lgkmcnt(4)
	v_mfma_f32_16x16x32_bf16 v[44:47], v[8:11], v[132:135], v[12:15]
	v_mfma_f32_16x16x32_bf16 v[12:15], v[212:215], v[128:131], v[172:175]
	v_mfma_f32_16x16x32_bf16 v[40:43], v[216:219], v[132:135], v[12:15]
	s_waitcnt lgkmcnt(3)
	v_mfma_f32_16x16x32_bf16 v[12:15], v[4:7], v[136:139], v[176:179]
	s_waitcnt lgkmcnt(2)
	v_mfma_f32_16x16x32_bf16 v[28:31], v[8:11], v[140:143], v[12:15]
	v_mfma_f32_16x16x32_bf16 v[12:15], v[212:215], v[136:139], v[180:183]
	s_waitcnt lgkmcnt(1)
	v_mfma_f32_16x16x32_bf16 v[4:7], v[4:7], v[236:239], v[16:19]
	v_mfma_f32_16x16x32_bf16 v[24:27], v[216:219], v[140:143], v[12:15]
	s_waitcnt lgkmcnt(0)
	v_mfma_f32_16x16x32_bf16 v[12:15], v[8:11], v[240:243], v[4:7]
	v_mfma_f32_16x16x32_bf16 v[4:7], v[212:215], v[236:239], v[20:23]
	v_mfma_f32_16x16x32_bf16 v[8:11], v[216:219], v[240:243], v[4:7]
	s_setprio 0
	s_setprio 1
	v_mfma_f32_16x16x32_bf16 v[4:7], v[220:223], v[32:35], v[184:187]
	v_mfma_f32_16x16x32_bf16 v[52:55], v[224:227], v[36:39], v[4:7]
	v_mfma_f32_16x16x32_bf16 v[4:7], v[228:231], v[32:35], v[188:191]
	v_mfma_f32_16x16x32_bf16 v[48:51], v[232:235], v[36:39], v[4:7]
	v_mfma_f32_16x16x32_bf16 v[4:7], v[220:223], v[128:131], v[192:195]
	v_mfma_f32_16x16x32_bf16 v[36:39], v[224:227], v[132:135], v[4:7]
	v_mfma_f32_16x16x32_bf16 v[4:7], v[228:231], v[128:131], v[196:199]
	v_mfma_f32_16x16x32_bf16 v[32:35], v[232:235], v[132:135], v[4:7]
	v_mfma_f32_16x16x32_bf16 v[4:7], v[220:223], v[136:139], v[200:203]
	v_mfma_f32_16x16x32_bf16 v[20:23], v[224:227], v[140:143], v[4:7]
	v_mfma_f32_16x16x32_bf16 v[4:7], v[228:231], v[136:139], v[204:207]
	v_mfma_f32_16x16x32_bf16 v[0:3], v[220:223], v[236:239], v[0:3]
	v_mfma_f32_16x16x32_bf16 v[16:19], v[232:235], v[140:143], v[4:7]
	v_mfma_f32_16x16x32_bf16 v[4:7], v[224:227], v[240:243], v[0:3]
	v_mfma_f32_16x16x32_bf16 v[0:3], v[228:231], v[236:239], v[208:211]
	v_mfma_f32_16x16x32_bf16 v[0:3], v[232:235], v[240:243], v[0:3]
	s_setprio 0
	s_barrier
	s_add_u32 s52, s48, 0x10000
	s_addc_u32 s53, s49, 0
	s_add_u32 s77, s80, 0x20000
	s_addc_u32 s78, s81, 0
	s_mov_b32 s79, 0
	.p2align	6

.LBB0_1405:
	s_ashr_i32 s41, s40, 31
	s_lshl_b64 s[42:43], s[40:41], 21
	s_add_u32 s42, s6, s42
	s_addc_u32 s43, s7, s43
	s_and_b64 s[44:45], s[0:1], exec
	s_cselect_b32 s41, s43, s3
	s_cselect_b32 s82, s42, s2
	s_ashr_i32 s39, s38, 31
	s_lshl_b64 s[44:45], s[38:39], 21
	v_readlane_b32 s50, v252, 62
	v_readlane_b32 s51, v252, 63
	s_add_u32 s44, s50, s44
	s_addc_u32 s45, s51, s45
	s_and_b64 s[52:53], s[0:1], exec
	s_cselect_b32 s39, s45, s57
	s_cselect_b32 s83, s44, s56
	s_add_u32 s52, s2, 0x18000
	s_addc_u32 s53, s3, 0
	s_waitcnt lgkmcnt(0)
	s_add_u32 s54, s56, 0x18000
	s_addc_u32 s55, s57, 0
	s_barrier
	s_setprio 1
	s_waitcnt lgkmcnt(7)
	v_mfma_f32_16x16x32_bf16 v[128:131], v[16:19], v[120:123], 0
	s_waitcnt lgkmcnt(6)
	v_mfma_f32_16x16x32_bf16 v[136:139], v[20:23], v[124:127], v[128:131]
	v_mfma_f32_16x16x32_bf16 v[128:131], v[24:27], v[120:123], 0
	v_mfma_f32_16x16x32_bf16 v[148:151], v[28:31], v[124:127], v[128:131]
	s_waitcnt lgkmcnt(5)
	v_mfma_f32_16x16x32_bf16 v[128:131], v[16:19], v[104:107], 0
	s_waitcnt lgkmcnt(4)
	v_mfma_f32_16x16x32_bf16 v[160:163], v[20:23], v[116:119], v[128:131]
	v_mfma_f32_16x16x32_bf16 v[128:131], v[24:27], v[104:107], 0
	v_mfma_f32_16x16x32_bf16 v[164:167], v[28:31], v[116:119], v[128:131]
	s_waitcnt lgkmcnt(3)
	v_mfma_f32_16x16x32_bf16 v[128:131], v[16:19], v[92:95], 0
	s_waitcnt lgkmcnt(1)
	v_mfma_f32_16x16x32_bf16 v[16:19], v[16:19], v[76:79], 0
	v_mfma_f32_16x16x32_bf16 v[168:171], v[20:23], v[100:103], v[128:131]
	s_waitcnt lgkmcnt(0)
	v_mfma_f32_16x16x32_bf16 v[16:19], v[20:23], v[80:83], v[16:19]
	v_mfma_f32_16x16x32_bf16 v[20:23], v[24:27], v[76:79], 0
	v_mfma_f32_16x16x32_bf16 v[128:131], v[24:27], v[92:95], 0
	v_mfma_f32_16x16x32_bf16 v[20:23], v[28:31], v[80:83], v[20:23]
	v_mfma_f32_16x16x32_bf16 v[172:175], v[28:31], v[100:103], v[128:131]
	s_setprio 0
	s_setprio 1
	v_mfma_f32_16x16x32_bf16 v[24:27], v[0:3], v[120:123], 0
	v_mfma_f32_16x16x32_bf16 v[176:179], v[4:7], v[124:127], v[24:27]
	v_mfma_f32_16x16x32_bf16 v[24:27], v[8:11], v[120:123], 0
	v_mfma_f32_16x16x32_bf16 v[180:183], v[12:15], v[124:127], v[24:27]
	v_mfma_f32_16x16x32_bf16 v[24:27], v[0:3], v[104:107], 0
	v_mfma_f32_16x16x32_bf16 v[184:187], v[4:7], v[116:119], v[24:27]
	v_mfma_f32_16x16x32_bf16 v[24:27], v[8:11], v[104:107], 0
	v_mfma_f32_16x16x32_bf16 v[192:195], v[12:15], v[116:119], v[24:27]
	v_mfma_f32_16x16x32_bf16 v[24:27], v[0:3], v[92:95], 0
	v_mfma_f32_16x16x32_bf16 v[0:3], v[0:3], v[76:79], 0
	v_mfma_f32_16x16x32_bf16 v[196:199], v[4:7], v[100:103], v[24:27]
	v_mfma_f32_16x16x32_bf16 v[24:27], v[8:11], v[92:95], 0
	v_mfma_f32_16x16x32_bf16 v[0:3], v[4:7], v[80:83], v[0:3]
	v_mfma_f32_16x16x32_bf16 v[4:7], v[8:11], v[76:79], 0
	v_mfma_f32_16x16x32_bf16 v[200:203], v[12:15], v[100:103], v[24:27]
	v_mfma_f32_16x16x32_bf16 v[204:207], v[12:15], v[80:83], v[4:7]
	s_setprio 0
	s_barrier
	v_add_u32_e32 v124, 0x18000, v211
	v_add_u32_e32 v125, 0x1c000, v211
	s_nop 1
	ds_read_b128 v[4:7], v124
	ds_read_b128 v[8:11], v124 offset:1024
	ds_read_b128 v[216:219], v124 offset:2048
	ds_read_b128 v[220:223], v124 offset:3072
	ds_read_b128 v[224:227], v125
	ds_read_b128 v[228:231], v125 offset:1024
	ds_read_b128 v[232:235], v125 offset:2048
	ds_read_b128 v[236:239], v125 offset:3072
	ds_read_b128 v[12:15], v214 offset:32768
	ds_read_b128 v[24:27], v214 offset:33792
	ds_read_b128 v[28:31], v214 offset:34816
	ds_read_b128 v[92:95], v214 offset:35840
	ds_read_b128 v[240:243], v214 offset:36864
	ds_read_b128 v[244:247], v214 offset:37888
	ds_read_b128 v[248:251], v214 offset:38912
	ds_read_b128 v[188:191], v214 offset:39936
	s_add_u32 s58, s2, 0x14000
	s_addc_u32 s59, s3, 0
	s_mov_b32 m0, s64
	s_nop 0
	global_load_lds_dwordx4 v210, s[58:59]
	s_add_u32 s58, s2, 0x16000
	s_addc_u32 s59, s3, 0
	s_mov_b32 m0, s65
	s_nop 0
	global_load_lds_dwordx4 v210, s[58:59]
	s_waitcnt vmcnt(8)
	s_waitcnt lgkmcnt(0)
	s_barrier
	s_setprio 1
	s_waitcnt lgkmcnt(7)
	v_mfma_f32_16x16x32_bf16 v[32:35], v[4:7], v[12:15], v[32:35]
	s_waitcnt lgkmcnt(6)
	v_mfma_f32_16x16x32_bf16 v[156:159], v[8:11], v[24:27], v[32:35]
	v_mfma_f32_16x16x32_bf16 v[32:35], v[216:219], v[12:15], v[36:39]
	v_mfma_f32_16x16x32_bf16 v[152:155], v[220:223], v[24:27], v[32:35]
	s_waitcnt lgkmcnt(5)
	v_mfma_f32_16x16x32_bf16 v[32:35], v[4:7], v[28:31], v[40:43]
	s_waitcnt lgkmcnt(4)
	v_mfma_f32_16x16x32_bf16 v[132:135], v[8:11], v[92:95], v[32:35]
	v_mfma_f32_16x16x32_bf16 v[32:35], v[216:219], v[28:31], v[44:47]
	v_mfma_f32_16x16x32_bf16 v[128:131], v[220:223], v[92:95], v[32:35]
	s_waitcnt lgkmcnt(3)
	v_mfma_f32_16x16x32_bf16 v[32:35], v[4:7], v[240:243], v[48:51]
	s_waitcnt lgkmcnt(2)
	v_mfma_f32_16x16x32_bf16 v[104:107], v[8:11], v[244:247], v[32:35]
	v_mfma_f32_16x16x32_bf16 v[32:35], v[216:219], v[240:243], v[52:55]
	v_mfma_f32_16x16x32_bf16 v[100:103], v[220:223], v[244:247], v[32:35]
	s_waitcnt lgkmcnt(1)
	v_mfma_f32_16x16x32_bf16 v[32:35], v[4:7], v[248:251], v[56:59]
	s_waitcnt lgkmcnt(0)
	v_mfma_f32_16x16x32_bf16 v[80:83], v[8:11], v[188:191], v[32:35]
	v_mfma_f32_16x16x32_bf16 v[32:35], v[216:219], v[248:251], v[60:63]
	v_mfma_f32_16x16x32_bf16 v[76:79], v[220:223], v[188:191], v[32:35]
	s_setprio 0
	s_setprio 1
	v_mfma_f32_16x16x32_bf16 v[32:35], v[224:227], v[12:15], v[64:67]
	v_mfma_f32_16x16x32_bf16 v[12:15], v[232:235], v[12:15], v[68:71]
	v_mfma_f32_16x16x32_bf16 v[140:143], v[236:239], v[24:27], v[12:15]
	v_mfma_f32_16x16x32_bf16 v[12:15], v[224:227], v[28:31], v[72:75]
	v_mfma_f32_16x16x32_bf16 v[120:123], v[228:231], v[92:95], v[12:15]
	v_mfma_f32_16x16x32_bf16 v[12:15], v[232:235], v[28:31], v[84:87]
	v_mfma_f32_16x16x32_bf16 v[116:119], v[236:239], v[92:95], v[12:15]
	v_mfma_f32_16x16x32_bf16 v[12:15], v[224:227], v[240:243], v[88:91]
	v_mfma_f32_16x16x32_bf16 v[92:95], v[228:231], v[244:247], v[12:15]
	v_mfma_f32_16x16x32_bf16 v[12:15], v[232:235], v[240:243], v[96:99]
	v_mfma_f32_16x16x32_bf16 v[88:91], v[236:239], v[244:247], v[12:15]
	v_mfma_f32_16x16x32_bf16 v[12:15], v[224:227], v[248:251], v[108:111]
	v_mfma_f32_16x16x32_bf16 v[68:71], v[228:231], v[188:191], v[12:15]
	v_mfma_f32_16x16x32_bf16 v[12:15], v[232:235], v[248:251], v[112:115]
	v_mfma_f32_16x16x32_bf16 v[144:147], v[228:231], v[24:27], v[32:35]
	v_mfma_f32_16x16x32_bf16 v[64:67], v[236:239], v[188:191], v[12:15]
	s_setprio 0
	s_barrier
	ds_read_b128 v[32:35], v214 offset:49152
	ds_read_b128 v[36:39], v214 offset:50176
	ds_read_b128 v[72:75], v214 offset:51200
	ds_read_b128 v[84:87], v214 offset:52224
	ds_read_b128 v[96:99], v214 offset:53248
	ds_read_b128 v[108:111], v214 offset:54272
	ds_read_b128 v[112:115], v214 offset:55296
	ds_read_b128 v[188:191], v214 offset:56320
	s_mov_b32 m0, s69
	s_nop 0
	global_load_lds_dwordx4 v210, s[54:55]
	s_add_u32 s54, s56, 0x1a000
	s_addc_u32 s55, s57, 0
	s_mov_b32 m0, s70
	s_nop 0
	global_load_lds_dwordx4 v210, s[54:55]
	s_add_u32 s54, s56, 0x1c000
	s_addc_u32 s55, s57, 0
	s_mov_b32 m0, s73
	s_nop 0
	global_load_lds_dwordx4 v210, s[54:55]
	s_add_u32 s54, s56, 0x1e000
	s_addc_u32 s55, s57, 0
	s_mov_b32 m0, s74
	s_nop 0
	global_load_lds_dwordx4 v210, s[54:55]
	s_nop 0
	s_mov_b32 m0, s71
	s_nop 0
	global_load_lds_dwordx4 v210, s[52:53]
	s_add_u32 s52, s2, 0x1a000
	s_addc_u32 s53, s3, 0
	s_mov_b32 m0, s72
	s_nop 0
	global_load_lds_dwordx4 v210, s[52:53]
	s_waitcnt vmcnt(8)
	s_waitcnt lgkmcnt(0)
	s_barrier
	s_setprio 1
	s_waitcnt lgkmcnt(7)
	v_mfma_f32_16x16x32_bf16 v[12:15], v[4:7], v[32:35], v[136:139]
	s_waitcnt lgkmcnt(6)
	v_mfma_f32_16x16x32_bf16 v[60:63], v[8:11], v[36:39], v[12:15]
	v_mfma_f32_16x16x32_bf16 v[12:15], v[216:219], v[32:35], v[148:151]
	v_mfma_f32_16x16x32_bf16 v[56:59], v[220:223], v[36:39], v[12:15]
	s_waitcnt lgkmcnt(5)
	v_mfma_f32_16x16x32_bf16 v[12:15], v[4:7], v[72:75], v[160:163]
	s_waitcnt lgkmcnt(4)
	v_mfma_f32_16x16x32_bf16 v[44:47], v[8:11], v[84:87], v[12:15]
	v_mfma_f32_16x16x32_bf16 v[12:15], v[216:219], v[72:75], v[164:167]
	v_mfma_f32_16x16x32_bf16 v[40:43], v[220:223], v[84:87], v[12:15]
	s_waitcnt lgkmcnt(3)
	v_mfma_f32_16x16x32_bf16 v[12:15], v[4:7], v[96:99], v[168:171]
	s_waitcnt lgkmcnt(2)
	v_mfma_f32_16x16x32_bf16 v[28:31], v[8:11], v[108:111], v[12:15]
	v_mfma_f32_16x16x32_bf16 v[12:15], v[216:219], v[96:99], v[172:175]
	s_waitcnt lgkmcnt(1)
	v_mfma_f32_16x16x32_bf16 v[4:7], v[4:7], v[112:115], v[16:19]
	v_mfma_f32_16x16x32_bf16 v[24:27], v[220:223], v[108:111], v[12:15]
	s_waitcnt lgkmcnt(0)
	v_mfma_f32_16x16x32_bf16 v[12:15], v[8:11], v[188:191], v[4:7]
	v_mfma_f32_16x16x32_bf16 v[4:7], v[216:219], v[112:115], v[20:23]
	v_mfma_f32_16x16x32_bf16 v[8:11], v[220:223], v[188:191], v[4:7]
	s_setprio 0
	s_setprio 1
	v_mfma_f32_16x16x32_bf16 v[4:7], v[224:227], v[32:35], v[176:179]
	v_mfma_f32_16x16x32_bf16 v[52:55], v[228:231], v[36:39], v[4:7]
	v_mfma_f32_16x16x32_bf16 v[4:7], v[232:235], v[32:35], v[180:183]
	v_mfma_f32_16x16x32_bf16 v[48:51], v[236:239], v[36:39], v[4:7]
	v_mfma_f32_16x16x32_bf16 v[4:7], v[224:227], v[72:75], v[184:187]
	v_mfma_f32_16x16x32_bf16 v[36:39], v[228:231], v[84:87], v[4:7]
	v_mfma_f32_16x16x32_bf16 v[4:7], v[232:235], v[72:75], v[192:195]
	v_mfma_f32_16x16x32_bf16 v[32:35], v[236:239], v[84:87], v[4:7]
	v_mfma_f32_16x16x32_bf16 v[4:7], v[224:227], v[96:99], v[196:199]
	v_mfma_f32_16x16x32_bf16 v[20:23], v[228:231], v[108:111], v[4:7]
	v_mfma_f32_16x16x32_bf16 v[4:7], v[232:235], v[96:99], v[200:203]
	v_mfma_f32_16x16x32_bf16 v[0:3], v[224:227], v[112:115], v[0:3]
	v_mfma_f32_16x16x32_bf16 v[16:19], v[236:239], v[108:111], v[4:7]
	v_mfma_f32_16x16x32_bf16 v[4:7], v[228:231], v[188:191], v[0:3]
	v_mfma_f32_16x16x32_bf16 v[0:3], v[232:235], v[112:115], v[204:207]
	v_mfma_f32_16x16x32_bf16 v[0:3], v[236:239], v[188:191], v[0:3]
	s_setprio 0
	s_barrier
	s_add_u32 s54, s2, 0x20000
	s_addc_u32 s55, s3, 0
	s_add_u32 s88, s56, 0x20000
	s_addc_u32 s89, s57, 0
	s_mov_b32 s90, 0
	.p2align	6

.LBB0_1504:
	s_ashr_i32 s45, s44, 31
	s_lshl_b64 s[46:47], s[44:45], 21
	s_add_u32 s46, s34, s46
	s_addc_u32 s47, s35, s47
	s_and_b64 s[48:49], s[0:1], exec
	s_cselect_b32 s45, s47, s3
	s_cselect_b32 s92, s46, s2
	s_ashr_i32 s43, s42, 31
	s_lshl_b64 s[48:49], s[42:43], 21
	v_readlane_b32 s12, v252, 58
	v_readlane_b32 s13, v252, 59
	s_add_u32 s48, s12, s48
	s_addc_u32 s49, s13, s49
	s_and_b64 s[52:53], s[0:1], exec
	s_cselect_b32 s43, s49, s59
	s_cselect_b32 s93, s48, s58
	s_add_u32 s52, s2, 0x18000
	s_addc_u32 s53, s3, 0
	s_waitcnt lgkmcnt(0)
	s_add_u32 s54, s58, 0x18000
	s_addc_u32 s55, s59, 0
	s_barrier
	s_setprio 1
	s_waitcnt lgkmcnt(7)
	v_mfma_f32_16x16x32_bf16 v[112:115], v[16:19], v[104:107], 0
	s_waitcnt lgkmcnt(6)
	v_mfma_f32_16x16x32_bf16 v[162:165], v[20:23], v[108:111], v[112:115]
	v_mfma_f32_16x16x32_bf16 v[112:115], v[24:27], v[104:107], 0
	v_mfma_f32_16x16x32_bf16 v[166:169], v[28:31], v[108:111], v[112:115]
	s_waitcnt lgkmcnt(5)
	v_mfma_f32_16x16x32_bf16 v[112:115], v[16:19], v[96:99], 0
	s_waitcnt lgkmcnt(4)
	v_mfma_f32_16x16x32_bf16 v[170:173], v[20:23], v[100:103], v[112:115]
	v_mfma_f32_16x16x32_bf16 v[112:115], v[24:27], v[96:99], 0
	v_mfma_f32_16x16x32_bf16 v[174:177], v[28:31], v[100:103], v[112:115]
	s_waitcnt lgkmcnt(3)
	v_mfma_f32_16x16x32_bf16 v[112:115], v[16:19], v[88:91], 0
	s_waitcnt lgkmcnt(1)
	v_mfma_f32_16x16x32_bf16 v[16:19], v[16:19], v[72:75], 0
	v_mfma_f32_16x16x32_bf16 v[178:181], v[20:23], v[92:95], v[112:115]
	s_waitcnt lgkmcnt(0)
	v_mfma_f32_16x16x32_bf16 v[16:19], v[20:23], v[76:79], v[16:19]
	v_mfma_f32_16x16x32_bf16 v[20:23], v[24:27], v[72:75], 0
	v_mfma_f32_16x16x32_bf16 v[112:115], v[24:27], v[88:91], 0
	v_mfma_f32_16x16x32_bf16 v[20:23], v[28:31], v[76:79], v[20:23]
	v_mfma_f32_16x16x32_bf16 v[182:185], v[28:31], v[92:95], v[112:115]
	s_setprio 0
	s_setprio 1
	v_mfma_f32_16x16x32_bf16 v[24:27], v[0:3], v[104:107], 0
	v_mfma_f32_16x16x32_bf16 v[186:189], v[4:7], v[108:111], v[24:27]
	v_mfma_f32_16x16x32_bf16 v[24:27], v[8:11], v[104:107], 0
	v_mfma_f32_16x16x32_bf16 v[190:193], v[12:15], v[108:111], v[24:27]
	v_mfma_f32_16x16x32_bf16 v[24:27], v[0:3], v[96:99], 0
	v_mfma_f32_16x16x32_bf16 v[194:197], v[4:7], v[100:103], v[24:27]
	v_mfma_f32_16x16x32_bf16 v[24:27], v[8:11], v[96:99], 0
	v_mfma_f32_16x16x32_bf16 v[198:201], v[12:15], v[100:103], v[24:27]
	v_mfma_f32_16x16x32_bf16 v[24:27], v[0:3], v[88:91], 0
	v_mfma_f32_16x16x32_bf16 v[0:3], v[0:3], v[72:75], 0
	v_mfma_f32_16x16x32_bf16 v[202:205], v[4:7], v[92:95], v[24:27]
	v_mfma_f32_16x16x32_bf16 v[24:27], v[8:11], v[88:91], 0
	v_mfma_f32_16x16x32_bf16 v[0:3], v[4:7], v[76:79], v[0:3]
	v_mfma_f32_16x16x32_bf16 v[4:7], v[8:11], v[72:75], 0
	v_mfma_f32_16x16x32_bf16 v[206:209], v[12:15], v[92:95], v[24:27]
	v_mfma_f32_16x16x32_bf16 v[210:213], v[12:15], v[76:79], v[4:7]
	s_setprio 0
	s_barrier
	v_add_u32_e32 v144, 0x18000, v155
	v_add_u32_e32 v150, 0x1c000, v155
	s_nop 1
	ds_read_b128 v[4:7], v144
	ds_read_b128 v[8:11], v144 offset:1024
	ds_read_b128 v[214:217], v144 offset:2048
	ds_read_b128 v[218:221], v144 offset:3072
	ds_read_b128 v[222:225], v150
	ds_read_b128 v[226:229], v150 offset:1024
	ds_read_b128 v[230:233], v150 offset:2048
	ds_read_b128 v[234:237], v150 offset:3072
	ds_read_b128 v[12:15], v158 offset:32768
	ds_read_b128 v[24:27], v158 offset:33792
	ds_read_b128 v[28:31], v158 offset:34816
	ds_read_b128 v[104:107], v158 offset:35840
	ds_read_b128 v[238:241], v158 offset:36864
	ds_read_b128 v[242:245], v158 offset:37888
	ds_read_b128 v[246:249], v158 offset:38912
	ds_read_b128 v[146:149], v158 offset:39936
	s_add_u32 s60, s2, 0x14000
	s_addc_u32 s61, s3, 0
	s_mov_b32 m0, s71
	s_nop 0
	global_load_lds_dwordx4 v154, s[60:61]
	s_add_u32 s60, s2, 0x16000
	s_addc_u32 s61, s3, 0
	s_mov_b32 m0, s72
	s_nop 0
	global_load_lds_dwordx4 v154, s[60:61]
	s_waitcnt vmcnt(8)
	s_waitcnt lgkmcnt(0)
	s_barrier
	s_setprio 1
	s_waitcnt lgkmcnt(7)
	v_mfma_f32_16x16x32_bf16 v[32:35], v[4:7], v[12:15], v[32:35]
	s_waitcnt lgkmcnt(6)
	v_mfma_f32_16x16x32_bf16 v[116:119], v[8:11], v[24:27], v[32:35]
	v_mfma_f32_16x16x32_bf16 v[32:35], v[214:217], v[12:15], v[36:39]
	v_mfma_f32_16x16x32_bf16 v[112:115], v[218:221], v[24:27], v[32:35]
	s_waitcnt lgkmcnt(5)
	v_mfma_f32_16x16x32_bf16 v[32:35], v[4:7], v[28:31], v[40:43]
	s_waitcnt lgkmcnt(4)
	v_mfma_f32_16x16x32_bf16 v[100:103], v[8:11], v[104:107], v[32:35]
	v_mfma_f32_16x16x32_bf16 v[32:35], v[214:217], v[28:31], v[44:47]
	v_mfma_f32_16x16x32_bf16 v[96:99], v[218:221], v[104:107], v[32:35]
	s_waitcnt lgkmcnt(3)
	v_mfma_f32_16x16x32_bf16 v[32:35], v[4:7], v[238:241], v[48:51]
	s_waitcnt lgkmcnt(2)
	v_mfma_f32_16x16x32_bf16 v[92:95], v[8:11], v[242:245], v[32:35]
	v_mfma_f32_16x16x32_bf16 v[32:35], v[214:217], v[238:241], v[52:55]
	v_mfma_f32_16x16x32_bf16 v[88:91], v[218:221], v[242:245], v[32:35]
	s_waitcnt lgkmcnt(1)
	v_mfma_f32_16x16x32_bf16 v[32:35], v[4:7], v[246:249], v[56:59]
	s_waitcnt lgkmcnt(0)
	v_mfma_f32_16x16x32_bf16 v[76:79], v[8:11], v[146:149], v[32:35]
	v_mfma_f32_16x16x32_bf16 v[32:35], v[214:217], v[246:249], v[60:63]
	v_mfma_f32_16x16x32_bf16 v[72:75], v[218:221], v[146:149], v[32:35]
	s_setprio 0
	s_setprio 1
	v_mfma_f32_16x16x32_bf16 v[32:35], v[222:225], v[12:15], v[64:67]
	v_mfma_f32_16x16x32_bf16 v[12:15], v[230:233], v[12:15], v[68:71]
	v_mfma_f32_16x16x32_bf16 v[120:123], v[234:237], v[24:27], v[12:15]
	v_mfma_f32_16x16x32_bf16 v[12:15], v[222:225], v[28:31], v[80:83]
	v_mfma_f32_16x16x32_bf16 v[108:111], v[226:229], v[104:107], v[12:15]
	v_mfma_f32_16x16x32_bf16 v[12:15], v[230:233], v[28:31], v[84:87]
	v_mfma_f32_16x16x32_bf16 v[104:107], v[234:237], v[104:107], v[12:15]
	v_mfma_f32_16x16x32_bf16 v[12:15], v[222:225], v[238:241], v[128:131]
	v_mfma_f32_16x16x32_bf16 v[84:87], v[226:229], v[242:245], v[12:15]
	v_mfma_f32_16x16x32_bf16 v[12:15], v[230:233], v[238:241], v[132:135]
	v_mfma_f32_16x16x32_bf16 v[80:83], v[234:237], v[242:245], v[12:15]
	v_mfma_f32_16x16x32_bf16 v[12:15], v[222:225], v[246:249], v[136:139]
	v_mfma_f32_16x16x32_bf16 v[68:71], v[226:229], v[146:149], v[12:15]
	v_mfma_f32_16x16x32_bf16 v[12:15], v[230:233], v[246:249], v[140:143]
	v_mfma_f32_16x16x32_bf16 v[124:127], v[226:229], v[24:27], v[32:35]
	v_mfma_f32_16x16x32_bf16 v[64:67], v[234:237], v[146:149], v[12:15]
	s_setprio 0
	s_barrier
	ds_read_b128 v[32:35], v158 offset:49152
	ds_read_b128 v[36:39], v158 offset:50176
	ds_read_b128 v[128:131], v158 offset:51200
	ds_read_b128 v[132:135], v158 offset:52224
	ds_read_b128 v[136:139], v158 offset:53248
	ds_read_b128 v[140:143], v158 offset:54272
	ds_read_b128 v[146:149], v158 offset:55296
	ds_read_b128 v[238:241], v158 offset:56320
	s_mov_b32 m0, s75
	s_nop 0
	global_load_lds_dwordx4 v154, s[54:55]
	s_add_u32 s54, s58, 0x1a000
	s_addc_u32 s55, s59, 0
	s_mov_b32 m0, s76
	s_nop 0
	global_load_lds_dwordx4 v154, s[54:55]
	s_add_u32 s54, s58, 0x1c000
	s_addc_u32 s55, s59, 0
	s_mov_b32 m0, s79
	s_nop 0
	global_load_lds_dwordx4 v154, s[54:55]
	s_add_u32 s54, s58, 0x1e000
	s_addc_u32 s55, s59, 0
	s_mov_b32 m0, s80
	s_nop 0
	global_load_lds_dwordx4 v154, s[54:55]
	s_nop 0
	s_mov_b32 m0, s77
	s_nop 0
	global_load_lds_dwordx4 v154, s[52:53]
	s_add_u32 s52, s2, 0x1a000
	s_addc_u32 s53, s3, 0
	s_mov_b32 m0, s78
	s_nop 0
	global_load_lds_dwordx4 v154, s[52:53]
	s_waitcnt vmcnt(8)
	s_waitcnt lgkmcnt(0)
	s_barrier
	s_setprio 1
	s_waitcnt lgkmcnt(7)
	v_mfma_f32_16x16x32_bf16 v[12:15], v[4:7], v[32:35], v[162:165]
	s_waitcnt lgkmcnt(6)
	v_mfma_f32_16x16x32_bf16 v[60:63], v[8:11], v[36:39], v[12:15]
	v_mfma_f32_16x16x32_bf16 v[12:15], v[214:217], v[32:35], v[166:169]
	v_mfma_f32_16x16x32_bf16 v[56:59], v[218:221], v[36:39], v[12:15]
	s_waitcnt lgkmcnt(5)
	v_mfma_f32_16x16x32_bf16 v[12:15], v[4:7], v[128:131], v[170:173]
	s_waitcnt lgkmcnt(4)
	v_mfma_f32_16x16x32_bf16 v[44:47], v[8:11], v[132:135], v[12:15]
	v_mfma_f32_16x16x32_bf16 v[12:15], v[214:217], v[128:131], v[174:177]
	v_mfma_f32_16x16x32_bf16 v[40:43], v[218:221], v[132:135], v[12:15]
	s_waitcnt lgkmcnt(3)
	v_mfma_f32_16x16x32_bf16 v[12:15], v[4:7], v[136:139], v[178:181]
	s_waitcnt lgkmcnt(2)
	v_mfma_f32_16x16x32_bf16 v[28:31], v[8:11], v[140:143], v[12:15]
	v_mfma_f32_16x16x32_bf16 v[12:15], v[214:217], v[136:139], v[182:185]
	s_waitcnt lgkmcnt(1)
	v_mfma_f32_16x16x32_bf16 v[4:7], v[4:7], v[146:149], v[16:19]
	v_mfma_f32_16x16x32_bf16 v[24:27], v[218:221], v[140:143], v[12:15]
	s_waitcnt lgkmcnt(0)
	v_mfma_f32_16x16x32_bf16 v[12:15], v[8:11], v[238:241], v[4:7]
	v_mfma_f32_16x16x32_bf16 v[4:7], v[214:217], v[146:149], v[20:23]
	v_mfma_f32_16x16x32_bf16 v[8:11], v[218:221], v[238:241], v[4:7]
	s_setprio 0
	s_setprio 1
	v_mfma_f32_16x16x32_bf16 v[4:7], v[222:225], v[32:35], v[186:189]
	v_mfma_f32_16x16x32_bf16 v[52:55], v[226:229], v[36:39], v[4:7]
	v_mfma_f32_16x16x32_bf16 v[4:7], v[230:233], v[32:35], v[190:193]
	v_mfma_f32_16x16x32_bf16 v[48:51], v[234:237], v[36:39], v[4:7]
	v_mfma_f32_16x16x32_bf16 v[4:7], v[222:225], v[128:131], v[194:197]
	v_mfma_f32_16x16x32_bf16 v[36:39], v[226:229], v[132:135], v[4:7]
	v_mfma_f32_16x16x32_bf16 v[4:7], v[230:233], v[128:131], v[198:201]
	v_mfma_f32_16x16x32_bf16 v[32:35], v[234:237], v[132:135], v[4:7]
	v_mfma_f32_16x16x32_bf16 v[4:7], v[222:225], v[136:139], v[202:205]
	v_mfma_f32_16x16x32_bf16 v[20:23], v[226:229], v[140:143], v[4:7]
	v_mfma_f32_16x16x32_bf16 v[4:7], v[230:233], v[136:139], v[206:209]
	v_mfma_f32_16x16x32_bf16 v[0:3], v[222:225], v[146:149], v[0:3]
	v_mfma_f32_16x16x32_bf16 v[16:19], v[234:237], v[140:143], v[4:7]
	v_mfma_f32_16x16x32_bf16 v[4:7], v[226:229], v[238:241], v[0:3]
	v_mfma_f32_16x16x32_bf16 v[0:3], v[230:233], v[146:149], v[210:213]
	v_mfma_f32_16x16x32_bf16 v[0:3], v[234:237], v[238:241], v[0:3]
	s_setprio 0
	s_barrier
	s_add_u32 s52, s2, 0x10000
	s_addc_u32 s53, s3, 0
	s_add_u32 s54, s58, 0x20000
	s_addc_u32 s55, s59, 0
	s_mov_b32 s96, 0
	.p2align	6

.LBB0_1538:
	s_ashr_i32 s39, s38, 31
	s_lshl_b64 s[42:43], s[38:39], 21
	v_readlane_b32 s44, v253, 6
	v_readlane_b32 s45, v253, 7
	s_add_u32 s42, s44, s42
	s_addc_u32 s43, s45, s43
	s_and_b64 s[44:45], s[12:13], exec
	s_cselect_b32 s39, s43, s47
	s_cselect_b32 s79, s42, s46
	s_ashr_i32 s15, s14, 31
	s_lshl_b64 s[44:45], s[14:15], 21
	v_readlane_b32 s48, v253, 4
	v_readlane_b32 s49, v253, 5
	s_add_u32 s44, s48, s44
	s_addc_u32 s45, s49, s45
	s_and_b64 s[48:49], s[12:13], exec
	s_cselect_b32 s15, s45, s3
	s_cselect_b32 s80, s44, s2
	s_add_u32 s48, s46, 0x18000
	s_addc_u32 s49, s47, 0
	s_waitcnt lgkmcnt(0)
	s_add_u32 s52, s2, 0x18000
	s_addc_u32 s53, s3, 0
	s_barrier
	s_setprio 1
	s_waitcnt lgkmcnt(7)
	v_mfma_f32_16x16x32_bf16 v[120:123], v[16:19], v[112:115], 0
	s_waitcnt lgkmcnt(6)
	v_mfma_f32_16x16x32_bf16 v[144:147], v[20:23], v[116:119], v[120:123]
	v_mfma_f32_16x16x32_bf16 v[120:123], v[24:27], v[112:115], 0
	v_mfma_f32_16x16x32_bf16 v[148:151], v[28:31], v[116:119], v[120:123]
	s_waitcnt lgkmcnt(5)
	v_mfma_f32_16x16x32_bf16 v[120:123], v[16:19], v[104:107], 0
	s_waitcnt lgkmcnt(4)
	v_mfma_f32_16x16x32_bf16 v[152:155], v[20:23], v[108:111], v[120:123]
	v_mfma_f32_16x16x32_bf16 v[120:123], v[24:27], v[104:107], 0
	v_mfma_f32_16x16x32_bf16 v[156:159], v[28:31], v[108:111], v[120:123]
	s_waitcnt lgkmcnt(3)
	v_mfma_f32_16x16x32_bf16 v[120:123], v[16:19], v[96:99], 0
	s_waitcnt lgkmcnt(1)
	v_mfma_f32_16x16x32_bf16 v[16:19], v[16:19], v[68:71], 0
	v_mfma_f32_16x16x32_bf16 v[160:163], v[20:23], v[100:103], v[120:123]
	s_waitcnt lgkmcnt(0)
	v_mfma_f32_16x16x32_bf16 v[16:19], v[20:23], v[84:87], v[16:19]
	v_mfma_f32_16x16x32_bf16 v[20:23], v[24:27], v[68:71], 0
	v_mfma_f32_16x16x32_bf16 v[120:123], v[24:27], v[96:99], 0
	v_mfma_f32_16x16x32_bf16 v[20:23], v[28:31], v[84:87], v[20:23]
	v_mfma_f32_16x16x32_bf16 v[164:167], v[28:31], v[100:103], v[120:123]
	s_setprio 0
	s_setprio 1
	v_mfma_f32_16x16x32_bf16 v[24:27], v[0:3], v[112:115], 0
	v_mfma_f32_16x16x32_bf16 v[168:171], v[4:7], v[116:119], v[24:27]
	v_mfma_f32_16x16x32_bf16 v[24:27], v[8:11], v[112:115], 0
	v_mfma_f32_16x16x32_bf16 v[172:175], v[12:15], v[116:119], v[24:27]
	v_mfma_f32_16x16x32_bf16 v[24:27], v[0:3], v[104:107], 0
	v_mfma_f32_16x16x32_bf16 v[176:179], v[4:7], v[108:111], v[24:27]
	v_mfma_f32_16x16x32_bf16 v[24:27], v[8:11], v[104:107], 0
	v_mfma_f32_16x16x32_bf16 v[180:183], v[12:15], v[108:111], v[24:27]
	v_mfma_f32_16x16x32_bf16 v[24:27], v[0:3], v[96:99], 0
	v_mfma_f32_16x16x32_bf16 v[0:3], v[0:3], v[68:71], 0
	v_mfma_f32_16x16x32_bf16 v[184:187], v[4:7], v[100:103], v[24:27]
	v_mfma_f32_16x16x32_bf16 v[24:27], v[8:11], v[96:99], 0
	v_mfma_f32_16x16x32_bf16 v[0:3], v[4:7], v[84:87], v[0:3]
	v_mfma_f32_16x16x32_bf16 v[4:7], v[8:11], v[68:71], 0
	v_mfma_f32_16x16x32_bf16 v[188:191], v[12:15], v[100:103], v[24:27]
	v_mfma_f32_16x16x32_bf16 v[192:195], v[12:15], v[84:87], v[4:7]
	s_setprio 0
	s_barrier
	v_add_u32_e32 v141, 0x18000, v137
	v_add_u32_e32 v142, 0x1c000, v137
	s_nop 1
	ds_read_b128 v[4:7], v141
	ds_read_b128 v[8:11], v141 offset:1024
	ds_read_b128 v[196:199], v141 offset:2048
	ds_read_b128 v[200:203], v141 offset:3072
	ds_read_b128 v[204:207], v142
	ds_read_b128 v[208:211], v142 offset:1024
	ds_read_b128 v[212:215], v142 offset:2048
	ds_read_b128 v[216:219], v142 offset:3072
	ds_read_b128 v[12:15], v140 offset:32768
	ds_read_b128 v[24:27], v140 offset:33792
	ds_read_b128 v[28:31], v140 offset:34816
	ds_read_b128 v[100:103], v140 offset:35840
	ds_read_b128 v[220:223], v140 offset:36864
	ds_read_b128 v[224:227], v140 offset:37888
	ds_read_b128 v[228:231], v140 offset:38912
	ds_read_b128 v[232:235], v140 offset:39936
	s_add_u32 s56, s46, 0x14000
	s_addc_u32 s57, s47, 0
	s_mov_b32 m0, s63
	s_nop 0
	global_load_lds_dwordx4 v136, s[56:57]
	s_add_u32 s56, s46, 0x16000
	s_addc_u32 s57, s47, 0
	s_mov_b32 m0, s64
	s_nop 0
	global_load_lds_dwordx4 v136, s[56:57]
	s_waitcnt vmcnt(8)
	s_waitcnt lgkmcnt(0)
	s_barrier
	s_setprio 1
	s_waitcnt lgkmcnt(7)
	v_mfma_f32_16x16x32_bf16 v[32:35], v[4:7], v[12:15], v[32:35]
	s_waitcnt lgkmcnt(6)
	v_mfma_f32_16x16x32_bf16 v[120:123], v[8:11], v[24:27], v[32:35]
	v_mfma_f32_16x16x32_bf16 v[32:35], v[196:199], v[12:15], v[36:39]
	v_mfma_f32_16x16x32_bf16 v[112:115], v[200:203], v[24:27], v[32:35]
	s_waitcnt lgkmcnt(5)
	v_mfma_f32_16x16x32_bf16 v[32:35], v[4:7], v[28:31], v[40:43]
	s_waitcnt lgkmcnt(4)
	v_mfma_f32_16x16x32_bf16 v[104:107], v[8:11], v[100:103], v[32:35]
	v_mfma_f32_16x16x32_bf16 v[32:35], v[196:199], v[28:31], v[44:47]
	v_mfma_f32_16x16x32_bf16 v[96:99], v[200:203], v[100:103], v[32:35]
	s_waitcnt lgkmcnt(3)
	v_mfma_f32_16x16x32_bf16 v[32:35], v[4:7], v[220:223], v[48:51]
	s_waitcnt lgkmcnt(2)
	v_mfma_f32_16x16x32_bf16 v[84:87], v[8:11], v[224:227], v[32:35]
	v_mfma_f32_16x16x32_bf16 v[32:35], v[196:199], v[220:223], v[52:55]
	v_mfma_f32_16x16x32_bf16 v[68:71], v[200:203], v[224:227], v[32:35]
	s_waitcnt lgkmcnt(1)
	v_mfma_f32_16x16x32_bf16 v[32:35], v[4:7], v[228:231], v[56:59]
	s_waitcnt lgkmcnt(0)
	v_mfma_f32_16x16x32_bf16 v[52:55], v[8:11], v[232:235], v[32:35]
	v_mfma_f32_16x16x32_bf16 v[32:35], v[196:199], v[228:231], v[60:63]
	v_mfma_f32_16x16x32_bf16 v[36:39], v[200:203], v[232:235], v[32:35]
	s_setprio 0
	s_setprio 1
	v_mfma_f32_16x16x32_bf16 v[32:35], v[204:207], v[12:15], v[64:67]
	v_mfma_f32_16x16x32_bf16 v[12:15], v[212:215], v[12:15], v[72:75]
	v_mfma_f32_16x16x32_bf16 v[116:119], v[216:219], v[24:27], v[12:15]
	v_mfma_f32_16x16x32_bf16 v[12:15], v[204:207], v[28:31], v[76:79]
	v_mfma_f32_16x16x32_bf16 v[108:111], v[208:211], v[100:103], v[12:15]
	v_mfma_f32_16x16x32_bf16 v[12:15], v[212:215], v[28:31], v[80:83]
	v_mfma_f32_16x16x32_bf16 v[100:103], v[216:219], v[100:103], v[12:15]
	v_mfma_f32_16x16x32_bf16 v[12:15], v[204:207], v[220:223], v[88:91]
	v_mfma_f32_16x16x32_bf16 v[88:91], v[208:211], v[224:227], v[12:15]
	v_mfma_f32_16x16x32_bf16 v[12:15], v[212:215], v[220:223], v[92:95]
	v_mfma_f32_16x16x32_bf16 v[72:75], v[216:219], v[224:227], v[12:15]
	v_mfma_f32_16x16x32_bf16 v[12:15], v[204:207], v[228:231], v[128:131]
	v_mfma_f32_16x16x32_bf16 v[56:59], v[208:211], v[232:235], v[12:15]
	v_mfma_f32_16x16x32_bf16 v[12:15], v[212:215], v[228:231], v[132:135]
	v_mfma_f32_16x16x32_bf16 v[124:127], v[208:211], v[24:27], v[32:35]
	v_mfma_f32_16x16x32_bf16 v[40:43], v[216:219], v[232:235], v[12:15]
	s_setprio 0
	s_barrier
	ds_read_b128 v[32:35], v140 offset:49152
	ds_read_b128 v[44:47], v140 offset:50176
	ds_read_b128 v[128:131], v140 offset:51200
	ds_read_b128 v[132:135], v140 offset:52224
	ds_read_b128 v[220:223], v140 offset:53248
	ds_read_b128 v[224:227], v140 offset:54272
	ds_read_b128 v[228:231], v140 offset:55296
	ds_read_b128 v[232:235], v140 offset:56320
	s_mov_b32 m0, s68
	s_nop 0
	global_load_lds_dwordx4 v136, s[52:53]
	s_add_u32 s52, s2, 0x1a000
	s_addc_u32 s53, s3, 0
	s_mov_b32 m0, s69
	s_nop 0
	global_load_lds_dwordx4 v136, s[52:53]
	s_add_u32 s52, s2, 0x1c000
	s_addc_u32 s53, s3, 0
	s_mov_b32 m0, s72
	s_nop 0
	global_load_lds_dwordx4 v136, s[52:53]
	s_add_u32 s52, s2, 0x1e000
	s_addc_u32 s53, s3, 0
	s_mov_b32 m0, s73
	s_nop 0
	global_load_lds_dwordx4 v136, s[52:53]
	s_nop 0
	s_mov_b32 m0, s70
	s_nop 0
	global_load_lds_dwordx4 v136, s[48:49]
	s_add_u32 s48, s46, 0x1a000
	s_addc_u32 s49, s47, 0
	s_mov_b32 m0, s71
	s_nop 0
	global_load_lds_dwordx4 v136, s[48:49]
	s_waitcnt vmcnt(8)
	s_waitcnt lgkmcnt(0)
	s_barrier
	s_setprio 1
	s_waitcnt lgkmcnt(7)
	v_mfma_f32_16x16x32_bf16 v[12:15], v[4:7], v[32:35], v[144:147]
	s_waitcnt lgkmcnt(6)
	v_mfma_f32_16x16x32_bf16 v[92:95], v[8:11], v[44:47], v[12:15]
	v_mfma_f32_16x16x32_bf16 v[12:15], v[196:199], v[32:35], v[148:151]
	v_mfma_f32_16x16x32_bf16 v[80:83], v[200:203], v[44:47], v[12:15]
	s_waitcnt lgkmcnt(5)
	v_mfma_f32_16x16x32_bf16 v[12:15], v[4:7], v[128:131], v[152:155]
	s_waitcnt lgkmcnt(4)
	v_mfma_f32_16x16x32_bf16 v[60:63], v[8:11], v[132:135], v[12:15]
	v_mfma_f32_16x16x32_bf16 v[12:15], v[196:199], v[128:131], v[156:159]
	v_mfma_f32_16x16x32_bf16 v[48:51], v[200:203], v[132:135], v[12:15]
	s_waitcnt lgkmcnt(3)
	v_mfma_f32_16x16x32_bf16 v[12:15], v[4:7], v[220:223], v[160:163]
	s_waitcnt lgkmcnt(2)
	v_mfma_f32_16x16x32_bf16 v[28:31], v[8:11], v[224:227], v[12:15]
	v_mfma_f32_16x16x32_bf16 v[12:15], v[196:199], v[220:223], v[164:167]
	s_waitcnt lgkmcnt(1)
	v_mfma_f32_16x16x32_bf16 v[4:7], v[4:7], v[228:231], v[16:19]
	v_mfma_f32_16x16x32_bf16 v[24:27], v[200:203], v[224:227], v[12:15]
	s_waitcnt lgkmcnt(0)
	v_mfma_f32_16x16x32_bf16 v[12:15], v[8:11], v[232:235], v[4:7]
	v_mfma_f32_16x16x32_bf16 v[4:7], v[196:199], v[228:231], v[20:23]
	v_mfma_f32_16x16x32_bf16 v[8:11], v[200:203], v[232:235], v[4:7]
	s_setprio 0
	s_setprio 1
	v_mfma_f32_16x16x32_bf16 v[4:7], v[204:207], v[32:35], v[168:171]
	v_mfma_f32_16x16x32_bf16 v[76:79], v[208:211], v[44:47], v[4:7]
	v_mfma_f32_16x16x32_bf16 v[4:7], v[212:215], v[32:35], v[172:175]
	v_mfma_f32_16x16x32_bf16 v[64:67], v[216:219], v[44:47], v[4:7]
	v_mfma_f32_16x16x32_bf16 v[4:7], v[204:207], v[128:131], v[176:179]
	v_mfma_f32_16x16x32_bf16 v[44:47], v[208:211], v[132:135], v[4:7]
	v_mfma_f32_16x16x32_bf16 v[4:7], v[212:215], v[128:131], v[180:183]
	v_mfma_f32_16x16x32_bf16 v[32:35], v[216:219], v[132:135], v[4:7]
	v_mfma_f32_16x16x32_bf16 v[4:7], v[204:207], v[220:223], v[184:187]
	v_mfma_f32_16x16x32_bf16 v[20:23], v[208:211], v[224:227], v[4:7]
	v_mfma_f32_16x16x32_bf16 v[4:7], v[212:215], v[220:223], v[188:191]
	v_mfma_f32_16x16x32_bf16 v[0:3], v[204:207], v[228:231], v[0:3]
	v_mfma_f32_16x16x32_bf16 v[16:19], v[216:219], v[224:227], v[4:7]
	v_mfma_f32_16x16x32_bf16 v[4:7], v[208:211], v[232:235], v[0:3]
	v_mfma_f32_16x16x32_bf16 v[0:3], v[212:215], v[228:231], v[192:195]
	v_mfma_f32_16x16x32_bf16 v[0:3], v[216:219], v[232:235], v[0:3]
	s_setprio 0
	s_barrier
	s_add_u32 s52, s46, 0x10000
	s_addc_u32 s53, s47, 0
	s_add_u32 s81, s2, 0x20000
	s_addc_u32 s82, s3, 0
	s_mov_b32 s83, 0
	.p2align	6

.LBB0_1674:
	s_ashr_i32 s43, s42, 31
	s_lshl_b64 s[44:45], s[42:43], 18
	s_add_u32 s44, s8, s44
	s_addc_u32 s45, s9, s45
	s_and_b64 s[46:47], s[0:1], exec
	s_cselect_b32 s43, s45, s3
	s_cselect_b32 s89, s44, s2
	s_ashr_i32 s41, s40, 31
	s_lshl_b64 s[46:47], s[40:41], 18
	v_readlane_b32 s50, v252, 60
	v_readlane_b32 s51, v252, 61
	s_add_u32 s46, s50, s46
	s_addc_u32 s47, s51, s47
	s_and_b64 s[52:53], s[0:1], exec
	s_cselect_b32 s41, s47, s59
	s_cselect_b32 s90, s46, s58
	s_add_u32 s52, s2, 0x18000
	s_addc_u32 s53, s3, 0
	s_waitcnt lgkmcnt(0)
	s_add_u32 s54, s58, 0x18000
	s_addc_u32 s55, s59, 0
	s_barrier
	s_setprio 1
	s_waitcnt lgkmcnt(7)
	v_mfma_f32_16x16x32_bf16 v[128:131], v[16:19], v[120:123], 0
	s_waitcnt lgkmcnt(6)
	v_mfma_f32_16x16x32_bf16 v[140:143], v[20:23], v[124:127], v[128:131]
	v_mfma_f32_16x16x32_bf16 v[128:131], v[24:27], v[120:123], 0
	v_mfma_f32_16x16x32_bf16 v[144:147], v[28:31], v[124:127], v[128:131]
	s_waitcnt lgkmcnt(5)
	v_mfma_f32_16x16x32_bf16 v[128:131], v[16:19], v[108:111], 0
	s_waitcnt lgkmcnt(4)
	v_mfma_f32_16x16x32_bf16 v[156:159], v[20:23], v[112:115], v[128:131]
	v_mfma_f32_16x16x32_bf16 v[128:131], v[24:27], v[108:111], 0
	v_mfma_f32_16x16x32_bf16 v[168:171], v[28:31], v[112:115], v[128:131]
	s_waitcnt lgkmcnt(3)
	v_mfma_f32_16x16x32_bf16 v[128:131], v[16:19], v[96:99], 0
	s_waitcnt lgkmcnt(1)
	v_mfma_f32_16x16x32_bf16 v[16:19], v[16:19], v[84:87], 0
	v_mfma_f32_16x16x32_bf16 v[172:175], v[20:23], v[100:103], v[128:131]
	s_waitcnt lgkmcnt(0)
	v_mfma_f32_16x16x32_bf16 v[16:19], v[20:23], v[88:91], v[16:19]
	v_mfma_f32_16x16x32_bf16 v[20:23], v[24:27], v[84:87], 0
	v_mfma_f32_16x16x32_bf16 v[128:131], v[24:27], v[96:99], 0
	v_mfma_f32_16x16x32_bf16 v[20:23], v[28:31], v[88:91], v[20:23]
	v_mfma_f32_16x16x32_bf16 v[176:179], v[28:31], v[100:103], v[128:131]
	s_setprio 0
	s_setprio 1
	v_mfma_f32_16x16x32_bf16 v[24:27], v[0:3], v[120:123], 0
	v_mfma_f32_16x16x32_bf16 v[180:183], v[4:7], v[124:127], v[24:27]
	v_mfma_f32_16x16x32_bf16 v[24:27], v[8:11], v[120:123], 0
	v_mfma_f32_16x16x32_bf16 v[184:187], v[12:15], v[124:127], v[24:27]
	v_mfma_f32_16x16x32_bf16 v[24:27], v[0:3], v[108:111], 0
	v_mfma_f32_16x16x32_bf16 v[194:197], v[4:7], v[112:115], v[24:27]
	v_mfma_f32_16x16x32_bf16 v[24:27], v[8:11], v[108:111], 0
	v_mfma_f32_16x16x32_bf16 v[198:201], v[12:15], v[112:115], v[24:27]
	v_mfma_f32_16x16x32_bf16 v[24:27], v[0:3], v[96:99], 0
	v_mfma_f32_16x16x32_bf16 v[0:3], v[0:3], v[84:87], 0
	v_mfma_f32_16x16x32_bf16 v[202:205], v[4:7], v[100:103], v[24:27]
	v_mfma_f32_16x16x32_bf16 v[24:27], v[8:11], v[96:99], 0
	v_mfma_f32_16x16x32_bf16 v[0:3], v[4:7], v[88:91], v[0:3]
	v_mfma_f32_16x16x32_bf16 v[4:7], v[8:11], v[84:87], 0
	v_mfma_f32_16x16x32_bf16 v[206:209], v[12:15], v[100:103], v[24:27]
	v_mfma_f32_16x16x32_bf16 v[218:221], v[12:15], v[88:91], v[4:7]
	s_setprio 0
	s_barrier
	v_add_u32_e32 v128, 0x18000, v213
	v_add_u32_e32 v129, 0x1c000, v213
	s_nop 1
	ds_read_b128 v[4:7], v128
	ds_read_b128 v[8:11], v128 offset:1024
	ds_read_b128 v[222:225], v128 offset:2048
	ds_read_b128 v[226:229], v128 offset:3072
	ds_read_b128 v[230:233], v129
	ds_read_b128 v[234:237], v129 offset:1024
	ds_read_b128 v[238:241], v129 offset:2048
	ds_read_b128 v[242:245], v129 offset:3072
	ds_read_b128 v[12:15], v216 offset:32768
	ds_read_b128 v[24:27], v216 offset:33792
	ds_read_b128 v[28:31], v216 offset:34816
	ds_read_b128 v[96:99], v216 offset:35840
	ds_read_b128 v[246:249], v216 offset:36864
	ds_read_b128 v[188:191], v216 offset:37888
	ds_read_b128 v[32:35], v216 offset:38912
	ds_read_b128 v[36:39], v216 offset:39936
	s_add_u32 s60, s2, 0x14000
	s_addc_u32 s61, s3, 0
	s_mov_b32 m0, s66
	s_nop 0
	global_load_lds_dwordx4 v212, s[60:61]
	s_add_u32 s60, s2, 0x16000
	s_addc_u32 s61, s3, 0
	s_mov_b32 m0, s67
	s_nop 0
	global_load_lds_dwordx4 v212, s[60:61]
	s_waitcnt vmcnt(8)
	s_waitcnt lgkmcnt(0)
	s_barrier
	s_setprio 1
	s_waitcnt lgkmcnt(7)
	v_mfma_f32_16x16x32_bf16 v[84:87], v[4:7], v[12:15], v[132:135]
	s_waitcnt lgkmcnt(5)
	v_mfma_f32_16x16x32_bf16 v[40:43], v[4:7], v[28:31], v[40:43]
	v_mfma_f32_16x16x32_bf16 v[164:167], v[8:11], v[24:27], v[84:87]
	v_mfma_f32_16x16x32_bf16 v[84:87], v[222:225], v[12:15], v[136:139]
	s_waitcnt lgkmcnt(4)
	v_mfma_f32_16x16x32_bf16 v[136:139], v[8:11], v[96:99], v[40:43]
	v_mfma_f32_16x16x32_bf16 v[40:43], v[222:225], v[28:31], v[44:47]
	v_mfma_f32_16x16x32_bf16 v[132:135], v[226:229], v[96:99], v[40:43]
	s_waitcnt lgkmcnt(3)
	v_mfma_f32_16x16x32_bf16 v[40:43], v[4:7], v[246:249], v[48:51]
	s_waitcnt lgkmcnt(2)
	v_mfma_f32_16x16x32_bf16 v[112:115], v[8:11], v[188:191], v[40:43]
	v_mfma_f32_16x16x32_bf16 v[40:43], v[222:225], v[246:249], v[52:55]
	v_mfma_f32_16x16x32_bf16 v[108:111], v[226:229], v[188:191], v[40:43]
	s_waitcnt lgkmcnt(1)
	v_mfma_f32_16x16x32_bf16 v[40:43], v[4:7], v[32:35], v[56:59]
	s_waitcnt lgkmcnt(0)
	v_mfma_f32_16x16x32_bf16 v[88:91], v[8:11], v[36:39], v[40:43]
	v_mfma_f32_16x16x32_bf16 v[40:43], v[222:225], v[32:35], v[60:63]
	v_mfma_f32_16x16x32_bf16 v[160:163], v[226:229], v[24:27], v[84:87]
	v_mfma_f32_16x16x32_bf16 v[84:87], v[226:229], v[36:39], v[40:43]
	s_setprio 0
	s_setprio 1
	v_mfma_f32_16x16x32_bf16 v[40:43], v[230:233], v[12:15], v[64:67]
	v_mfma_f32_16x16x32_bf16 v[12:15], v[238:241], v[12:15], v[68:71]
	v_mfma_f32_16x16x32_bf16 v[148:151], v[242:245], v[24:27], v[12:15]
	v_mfma_f32_16x16x32_bf16 v[12:15], v[230:233], v[28:31], v[72:75]
	v_mfma_f32_16x16x32_bf16 v[124:127], v[234:237], v[96:99], v[12:15]
	v_mfma_f32_16x16x32_bf16 v[12:15], v[238:241], v[28:31], v[76:79]
	v_mfma_f32_16x16x32_bf16 v[120:123], v[242:245], v[96:99], v[12:15]
	v_mfma_f32_16x16x32_bf16 v[12:15], v[230:233], v[246:249], v[80:83]
	v_mfma_f32_16x16x32_bf16 v[100:103], v[234:237], v[188:191], v[12:15]
	v_mfma_f32_16x16x32_bf16 v[12:15], v[238:241], v[246:249], v[92:95]
	v_mfma_f32_16x16x32_bf16 v[96:99], v[242:245], v[188:191], v[12:15]
	v_mfma_f32_16x16x32_bf16 v[12:15], v[230:233], v[32:35], v[104:107]
	v_mfma_f32_16x16x32_bf16 v[76:79], v[234:237], v[36:39], v[12:15]
	v_mfma_f32_16x16x32_bf16 v[12:15], v[238:241], v[32:35], v[116:119]
	v_mfma_f32_16x16x32_bf16 v[152:155], v[234:237], v[24:27], v[40:43]
	v_mfma_f32_16x16x32_bf16 v[72:75], v[242:245], v[36:39], v[12:15]
	s_setprio 0
	s_barrier
	ds_read_b128 v[32:35], v216 offset:49152
	ds_read_b128 v[36:39], v216 offset:50176
	ds_read_b128 v[48:51], v216 offset:51200
	ds_read_b128 v[64:67], v216 offset:52224
	ds_read_b128 v[80:83], v216 offset:53248
	ds_read_b128 v[92:95], v216 offset:54272
	ds_read_b128 v[104:107], v216 offset:55296
	ds_read_b128 v[116:119], v216 offset:56320
	s_mov_b32 m0, s71
	s_nop 0
	global_load_lds_dwordx4 v212, s[54:55]
	s_add_u32 s54, s58, 0x1a000
	s_addc_u32 s55, s59, 0
	s_mov_b32 m0, s72
	s_nop 0
	global_load_lds_dwordx4 v212, s[54:55]
	s_add_u32 s54, s58, 0x1c000
	s_addc_u32 s55, s59, 0
	s_mov_b32 m0, s75
	s_nop 0
	global_load_lds_dwordx4 v212, s[54:55]
	s_add_u32 s54, s58, 0x1e000
	s_addc_u32 s55, s59, 0
	s_mov_b32 m0, s76
	s_nop 0
	global_load_lds_dwordx4 v212, s[54:55]
	s_nop 0
	s_mov_b32 m0, s73
	s_nop 0
	global_load_lds_dwordx4 v212, s[52:53]
	s_add_u32 s52, s2, 0x1a000
	s_addc_u32 s53, s3, 0
	s_mov_b32 m0, s74
	s_nop 0
	global_load_lds_dwordx4 v212, s[52:53]
	s_waitcnt vmcnt(8)
	s_waitcnt lgkmcnt(0)
	s_barrier
	s_setprio 1
	s_waitcnt lgkmcnt(7)
	v_mfma_f32_16x16x32_bf16 v[12:15], v[4:7], v[32:35], v[140:143]
	s_waitcnt lgkmcnt(6)
	v_mfma_f32_16x16x32_bf16 v[68:71], v[8:11], v[36:39], v[12:15]
	v_mfma_f32_16x16x32_bf16 v[12:15], v[222:225], v[32:35], v[144:147]
	v_mfma_f32_16x16x32_bf16 v[60:63], v[226:229], v[36:39], v[12:15]
	s_waitcnt lgkmcnt(5)
	v_mfma_f32_16x16x32_bf16 v[12:15], v[4:7], v[48:51], v[156:159]
	s_waitcnt lgkmcnt(4)
	v_mfma_f32_16x16x32_bf16 v[44:47], v[8:11], v[64:67], v[12:15]
	v_mfma_f32_16x16x32_bf16 v[12:15], v[222:225], v[48:51], v[168:171]
	v_mfma_f32_16x16x32_bf16 v[40:43], v[226:229], v[64:67], v[12:15]
	s_waitcnt lgkmcnt(3)
	v_mfma_f32_16x16x32_bf16 v[12:15], v[4:7], v[80:83], v[172:175]
	s_waitcnt lgkmcnt(2)
	v_mfma_f32_16x16x32_bf16 v[28:31], v[8:11], v[92:95], v[12:15]
	v_mfma_f32_16x16x32_bf16 v[12:15], v[222:225], v[80:83], v[176:179]
	s_waitcnt lgkmcnt(1)
	v_mfma_f32_16x16x32_bf16 v[4:7], v[4:7], v[104:107], v[16:19]
	v_mfma_f32_16x16x32_bf16 v[24:27], v[226:229], v[92:95], v[12:15]
	s_waitcnt lgkmcnt(0)
	v_mfma_f32_16x16x32_bf16 v[12:15], v[8:11], v[116:119], v[4:7]
	v_mfma_f32_16x16x32_bf16 v[4:7], v[222:225], v[104:107], v[20:23]
	v_mfma_f32_16x16x32_bf16 v[8:11], v[226:229], v[116:119], v[4:7]
	s_setprio 0
	s_setprio 1
	v_mfma_f32_16x16x32_bf16 v[4:7], v[230:233], v[32:35], v[180:183]
	v_mfma_f32_16x16x32_bf16 v[56:59], v[234:237], v[36:39], v[4:7]
	v_mfma_f32_16x16x32_bf16 v[4:7], v[238:241], v[32:35], v[184:187]
	v_mfma_f32_16x16x32_bf16 v[52:55], v[242:245], v[36:39], v[4:7]
	v_mfma_f32_16x16x32_bf16 v[4:7], v[230:233], v[48:51], v[194:197]
	v_mfma_f32_16x16x32_bf16 v[36:39], v[234:237], v[64:67], v[4:7]
	v_mfma_f32_16x16x32_bf16 v[4:7], v[238:241], v[48:51], v[198:201]
	v_mfma_f32_16x16x32_bf16 v[32:35], v[242:245], v[64:67], v[4:7]
	v_mfma_f32_16x16x32_bf16 v[4:7], v[230:233], v[80:83], v[202:205]
	v_mfma_f32_16x16x32_bf16 v[20:23], v[234:237], v[92:95], v[4:7]
	v_mfma_f32_16x16x32_bf16 v[4:7], v[238:241], v[80:83], v[206:209]
	v_mfma_f32_16x16x32_bf16 v[0:3], v[230:233], v[104:107], v[0:3]
	v_mfma_f32_16x16x32_bf16 v[16:19], v[242:245], v[92:95], v[4:7]
	v_mfma_f32_16x16x32_bf16 v[4:7], v[234:237], v[116:119], v[0:3]
	v_mfma_f32_16x16x32_bf16 v[0:3], v[238:241], v[104:107], v[218:221]
	v_mfma_f32_16x16x32_bf16 v[0:3], v[242:245], v[116:119], v[0:3]
	s_setprio 0
	s_barrier
	s_add_u32 s54, s2, 0x20000
	s_addc_u32 s55, s3, 0
	s_add_u32 s91, s58, 0x20000
	s_addc_u32 s92, s59, 0
	s_mov_b32 s93, 0
	.p2align	6

.LBB0_1767:
	s_ashr_i32 s43, s42, 31
	s_lshl_b64 s[44:45], s[42:43], 20
	s_add_u32 s44, s6, s44
	s_addc_u32 s45, s7, s45
	s_and_b64 s[46:47], s[0:1], exec
	s_cselect_b32 s5, s45, s57
	s_cselect_b32 s43, s44, s56
	s_ashr_i32 s41, s40, 31
	s_lshl_b64 s[46:47], s[40:41], 20
	v_readlane_b32 s8, v253, 2
	s_add_u32 s46, s8, s46
	v_readlane_b32 s8, v253, 3
	s_addc_u32 s47, s8, s47
	s_and_b64 s[58:59], s[0:1], exec
	s_cselect_b32 s41, s47, s3
	s_cselect_b32 s49, s46, s2
	s_add_u32 s92, s2, 0x10000
	v_mov_b32_e32 v0, 0
	s_addc_u32 s93, s3, 0
	s_mov_b32 s96, -2
	v_mov_b32_e32 v1, v0
	v_mov_b32_e32 v2, v0
	v_mov_b32_e32 v3, v0
	v_mov_b32_e32 v8, v0
	v_mov_b32_e32 v9, v0
	v_mov_b32_e32 v10, v0
	v_mov_b32_e32 v11, v0
	v_mov_b32_e32 v16, v0
	v_mov_b32_e32 v17, v0
	v_mov_b32_e32 v18, v0
	v_mov_b32_e32 v19, v0
	v_mov_b32_e32 v24, v0
	v_mov_b32_e32 v25, v0
	v_mov_b32_e32 v26, v0
	v_mov_b32_e32 v27, v0
	v_mov_b32_e32 v32, v0
	v_mov_b32_e32 v33, v0
	v_mov_b32_e32 v34, v0
	v_mov_b32_e32 v35, v0
	v_mov_b32_e32 v40, v0
	v_mov_b32_e32 v41, v0
	v_mov_b32_e32 v42, v0
	v_mov_b32_e32 v43, v0
	v_mov_b32_e32 v52, v0
	v_mov_b32_e32 v53, v0
	v_mov_b32_e32 v54, v0
	v_mov_b32_e32 v55, v0
	v_mov_b32_e32 v60, v0
	v_mov_b32_e32 v61, v0
	v_mov_b32_e32 v62, v0
	v_mov_b32_e32 v63, v0
	v_mov_b32_e32 v4, v0
	v_mov_b32_e32 v5, v0
	v_mov_b32_e32 v6, v0
	v_mov_b32_e32 v7, v0
	v_mov_b32_e32 v12, v0
	v_mov_b32_e32 v13, v0
	v_mov_b32_e32 v14, v0
	v_mov_b32_e32 v15, v0
	v_mov_b32_e32 v20, v0
	v_mov_b32_e32 v21, v0
	v_mov_b32_e32 v22, v0
	v_mov_b32_e32 v23, v0
	v_mov_b32_e32 v28, v0
	v_mov_b32_e32 v29, v0
	v_mov_b32_e32 v30, v0
	v_mov_b32_e32 v31, v0
	v_mov_b32_e32 v36, v0
	v_mov_b32_e32 v37, v0
	v_mov_b32_e32 v38, v0
	v_mov_b32_e32 v39, v0
	v_mov_b32_e32 v44, v0
	v_mov_b32_e32 v45, v0
	v_mov_b32_e32 v46, v0
	v_mov_b32_e32 v47, v0
	v_mov_b32_e32 v48, v0
	v_mov_b32_e32 v49, v0
	v_mov_b32_e32 v50, v0
	v_mov_b32_e32 v51, v0
	v_mov_b32_e32 v56, v0
	v_mov_b32_e32 v57, v0
	v_mov_b32_e32 v58, v0
	v_mov_b32_e32 v59, v0
	v_mov_b32_e32 v64, v0
	v_mov_b32_e32 v65, v0
	v_mov_b32_e32 v66, v0
	v_mov_b32_e32 v67, v0
	v_mov_b32_e32 v72, v0
	v_mov_b32_e32 v73, v0
	v_mov_b32_e32 v74, v0
	v_mov_b32_e32 v75, v0
	v_mov_b32_e32 v80, v0
	v_mov_b32_e32 v81, v0
	v_mov_b32_e32 v82, v0
	v_mov_b32_e32 v83, v0
	v_mov_b32_e32 v88, v0
	v_mov_b32_e32 v89, v0
	v_mov_b32_e32 v90, v0
	v_mov_b32_e32 v91, v0
	v_mov_b32_e32 v96, v0
	v_mov_b32_e32 v97, v0
	v_mov_b32_e32 v98, v0
	v_mov_b32_e32 v99, v0
	v_mov_b32_e32 v104, v0
	v_mov_b32_e32 v105, v0
	v_mov_b32_e32 v106, v0
	v_mov_b32_e32 v107, v0
	v_mov_b32_e32 v112, v0
	v_mov_b32_e32 v113, v0
	v_mov_b32_e32 v114, v0
	v_mov_b32_e32 v115, v0
	v_mov_b32_e32 v120, v0
	v_mov_b32_e32 v121, v0
	v_mov_b32_e32 v122, v0
	v_mov_b32_e32 v123, v0
	v_mov_b32_e32 v68, v0
	v_mov_b32_e32 v69, v0
	v_mov_b32_e32 v70, v0
	v_mov_b32_e32 v71, v0
	v_mov_b32_e32 v76, v0
	v_mov_b32_e32 v77, v0
	v_mov_b32_e32 v78, v0
	v_mov_b32_e32 v79, v0
	v_mov_b32_e32 v84, v0
	v_mov_b32_e32 v85, v0
	v_mov_b32_e32 v86, v0
	v_mov_b32_e32 v87, v0
	v_mov_b32_e32 v92, v0
	v_mov_b32_e32 v93, v0
	v_mov_b32_e32 v94, v0
	v_mov_b32_e32 v95, v0
	v_mov_b32_e32 v100, v0
	v_mov_b32_e32 v101, v0
	v_mov_b32_e32 v102, v0
	v_mov_b32_e32 v103, v0
	v_mov_b32_e32 v108, v0
	v_mov_b32_e32 v109, v0
	v_mov_b32_e32 v110, v0
	v_mov_b32_e32 v111, v0
	v_mov_b32_e32 v116, v0
	v_mov_b32_e32 v117, v0
	v_mov_b32_e32 v118, v0
	v_mov_b32_e32 v119, v0
	v_mov_b32_e32 v124, v0
	v_mov_b32_e32 v125, v0
	v_mov_b32_e32 v126, v0
	v_mov_b32_e32 v127, v0
	.p2align	6

.LBB0_1952:
	s_mul_i32 s17, s27, 0x280000
	s_mul_hi_u32 s19, s26, 0x280000
	s_add_i32 s19, s19, s17
	s_mul_i32 s17, s26, 0x280000
	v_mbcnt_lo_u32_b32 v0, -1, 0
	v_mbcnt_hi_u32_b32 v0, -1, v0
	s_add_u32 s26, s84, s17
	s_waitcnt lgkmcnt(0)
	v_and_b32_e32 v1, 15, v0
	v_or_b32_e32 v2, s59, v1
	v_lshlrev_b32_e32 v5, 4, v0
	s_addc_u32 s27, s85, s19
	s_mul_i32 s17, s39, 0x280000
	s_mul_hi_u32 s19, s38, 0x280000
	v_lshlrev_b32_e32 v3, 6, v2
	v_and_b32_e32 v4, 48, v0
	v_and_b32_e32 v5, 0xfffffc00, v5
	v_lshlrev_b32_e32 v2, 2, v2
	s_add_i32 s17, s19, s17
	s_mul_i32 s19, s38, 0x280000
	v_readlane_b32 s23, v253, 0
	v_and_or_b32 v3, v3, s73, v4
	v_add_u32_e32 v6, s60, v5
	v_and_b32_e32 v2, 32, v2
	v_lshlrev_b32_e32 v0, 2, v0
	s_add_u32 s23, s23, s19
	v_readlane_b32 s25, v253, 1
	v_bitop3_b32 v2, v3, v6, v2 bitop3:0xde
	v_lshl_or_b32 v1, v1, 6, v4
	v_add_u32_e32 v3, s62, v5
	v_and_b32_e32 v0, 32, v0
	s_addc_u32 s25, s25, s17
	v_bitop3_b32 v1, v1, v3, v0 bitop3:0xde
	s_add_u32 s75, s2, 0x10000
	v_mov_b32_e32 v0, 0
	v_add_u32_e32 v1, 0, v1
	s_addc_u32 s76, s3, 0
	s_mov_b32 s77, -2
	v_add_u32_e32 v128, 0x10000, v1
	v_add_u32_e32 v129, 0x14000, v1
	v_add_u32_e32 v130, 0, v2
	v_add_u32_e32 v131, 0x18000, v1
	v_add_u32_e32 v132, 0x1c000, v1
	v_mov_b32_e32 v1, v0
	v_mov_b32_e32 v2, v0
	v_mov_b32_e32 v3, v0
	v_mov_b32_e32 v4, v0
	v_mov_b32_e32 v5, v0
	v_mov_b32_e32 v6, v0
	v_mov_b32_e32 v7, v0
	v_mov_b32_e32 v16, v0
	v_mov_b32_e32 v17, v0
	v_mov_b32_e32 v18, v0
	v_mov_b32_e32 v19, v0
	v_mov_b32_e32 v20, v0
	v_mov_b32_e32 v21, v0
	v_mov_b32_e32 v22, v0
	v_mov_b32_e32 v23, v0
	v_mov_b32_e32 v32, v0
	v_mov_b32_e32 v33, v0
	v_mov_b32_e32 v34, v0
	v_mov_b32_e32 v35, v0
	v_mov_b32_e32 v36, v0
	v_mov_b32_e32 v37, v0
	v_mov_b32_e32 v38, v0
	v_mov_b32_e32 v39, v0
	v_mov_b32_e32 v48, v0
	v_mov_b32_e32 v49, v0
	v_mov_b32_e32 v50, v0
	v_mov_b32_e32 v51, v0
	v_mov_b32_e32 v52, v0
	v_mov_b32_e32 v53, v0
	v_mov_b32_e32 v54, v0
	v_mov_b32_e32 v55, v0
	v_mov_b32_e32 v8, v0
	v_mov_b32_e32 v9, v0
	v_mov_b32_e32 v10, v0
	v_mov_b32_e32 v11, v0
	v_mov_b32_e32 v12, v0
	v_mov_b32_e32 v13, v0
	v_mov_b32_e32 v14, v0
	v_mov_b32_e32 v15, v0
	v_mov_b32_e32 v24, v0
	v_mov_b32_e32 v25, v0
	v_mov_b32_e32 v26, v0
	v_mov_b32_e32 v27, v0
	v_mov_b32_e32 v28, v0
	v_mov_b32_e32 v29, v0
	v_mov_b32_e32 v30, v0
	v_mov_b32_e32 v31, v0
	v_mov_b32_e32 v40, v0
	v_mov_b32_e32 v41, v0
	v_mov_b32_e32 v42, v0
	v_mov_b32_e32 v43, v0
	v_mov_b32_e32 v44, v0
	v_mov_b32_e32 v45, v0
	v_mov_b32_e32 v46, v0
	v_mov_b32_e32 v47, v0
	v_mov_b32_e32 v56, v0
	v_mov_b32_e32 v57, v0
	v_mov_b32_e32 v58, v0
	v_mov_b32_e32 v59, v0
	v_mov_b32_e32 v60, v0
	v_mov_b32_e32 v61, v0
	v_mov_b32_e32 v62, v0
	v_mov_b32_e32 v63, v0
	v_mov_b32_e32 v64, v0
	v_mov_b32_e32 v65, v0
	v_mov_b32_e32 v66, v0
	v_mov_b32_e32 v67, v0
	v_mov_b32_e32 v68, v0
	v_mov_b32_e32 v69, v0
	v_mov_b32_e32 v70, v0
	v_mov_b32_e32 v71, v0
	v_mov_b32_e32 v80, v0
	v_mov_b32_e32 v81, v0
	v_mov_b32_e32 v82, v0
	v_mov_b32_e32 v83, v0
	v_mov_b32_e32 v84, v0
	v_mov_b32_e32 v85, v0
	v_mov_b32_e32 v86, v0
	v_mov_b32_e32 v87, v0
	v_mov_b32_e32 v96, v0
	v_mov_b32_e32 v97, v0
	v_mov_b32_e32 v98, v0
	v_mov_b32_e32 v99, v0
	v_mov_b32_e32 v100, v0
	v_mov_b32_e32 v101, v0
	v_mov_b32_e32 v102, v0
	v_mov_b32_e32 v103, v0
	v_mov_b32_e32 v112, v0
	v_mov_b32_e32 v113, v0
	v_mov_b32_e32 v114, v0
	v_mov_b32_e32 v115, v0
	v_mov_b32_e32 v116, v0
	v_mov_b32_e32 v117, v0
	v_mov_b32_e32 v118, v0
	v_mov_b32_e32 v119, v0
	v_mov_b32_e32 v72, v0
	v_mov_b32_e32 v73, v0
	v_mov_b32_e32 v74, v0
	v_mov_b32_e32 v75, v0
	v_mov_b32_e32 v76, v0
	v_mov_b32_e32 v77, v0
	v_mov_b32_e32 v78, v0
	v_mov_b32_e32 v79, v0
	v_mov_b32_e32 v88, v0
	v_mov_b32_e32 v89, v0
	v_mov_b32_e32 v90, v0
	v_mov_b32_e32 v91, v0
	v_mov_b32_e32 v92, v0
	v_mov_b32_e32 v93, v0
	v_mov_b32_e32 v94, v0
	v_mov_b32_e32 v95, v0
	v_mov_b32_e32 v104, v0
	v_mov_b32_e32 v105, v0
	v_mov_b32_e32 v106, v0
	v_mov_b32_e32 v107, v0
	v_mov_b32_e32 v108, v0
	v_mov_b32_e32 v109, v0
	v_mov_b32_e32 v110, v0
	v_mov_b32_e32 v111, v0
	v_mov_b32_e32 v120, v0
	v_mov_b32_e32 v121, v0
	v_mov_b32_e32 v122, v0
	v_mov_b32_e32 v123, v0
	v_mov_b32_e32 v124, v0
	v_mov_b32_e32 v125, v0
	v_mov_b32_e32 v126, v0
	v_mov_b32_e32 v127, v0
	.p2align	6
.LBB0_1953:
	ds_read_b128 v[134:137], v128
	ds_read_b128 v[138:141], v128 offset:1024
	ds_read_b128 v[142:145], v128 offset:2048
	ds_read_b128 v[146:149], v128 offset:3072
	ds_read_b128 v[150:153], v129
	ds_read_b128 v[154:157], v129 offset:1024
	ds_read_b128 v[158:161], v129 offset:2048
	ds_read_b128 v[162:165], v129 offset:3072
	s_add_u32 s2, s28, 0x10000
	s_addc_u32 s3, s29, 0
	s_cmp_eq_u32 s77, 8
	s_cselect_b32 s38, s26, s2
	s_cselect_b32 s39, s27, s3
	s_cselect_b32 s42, s23, s75
	s_cselect_b32 s43, s25, s76
	s_add_u32 s40, s38, 0x8000
	s_addc_u32 s41, s39, 0
	ds_read_b128 v[166:169], v130
	ds_read_b128 v[170:173], v130 offset:1024
	ds_read_b128 v[174:177], v130 offset:2048
	ds_read_b128 v[178:181], v130 offset:3072
	ds_read_b128 v[182:185], v130 offset:4096
	ds_read_b128 v[192:195], v130 offset:5120
	ds_read_b128 v[196:199], v130 offset:6144
	ds_read_b128 v[200:203], v130 offset:7168
	s_add_u32 s78, s28, 0xc000
	s_addc_u32 s79, s29, 0
	s_mov_b32 m0, s63
	s_nop 0
	global_load_lds_dwordx4 v210, s[78:79]
	s_add_u32 s28, s28, 0xe000
	s_addc_u32 s29, s29, 0
	s_mov_b32 m0, s66
	s_nop 0
	global_load_lds_dwordx4 v210, s[28:29]
	s_waitcnt vmcnt(8)
	s_waitcnt lgkmcnt(0)
	s_barrier
	s_setprio 1
	s_waitcnt lgkmcnt(7)
	s_waitcnt lgkmcnt(0)
	v_mfma_f32_16x16x32_bf16 v[124:127], v[134:137], v[166:169], v[124:127]
	v_mfma_f32_16x16x32_bf16 v[124:127], v[138:141], v[170:173], v[124:127]
	v_mfma_f32_16x16x32_bf16 v[108:111], v[134:137], v[174:177], v[108:111]
	v_mfma_f32_16x16x32_bf16 v[108:111], v[138:141], v[178:181], v[108:111]
	v_mfma_f32_16x16x32_bf16 v[92:95], v[134:137], v[182:185], v[92:95]
	v_mfma_f32_16x16x32_bf16 v[92:95], v[138:141], v[192:195], v[92:95]
	v_mfma_f32_16x16x32_bf16 v[76:79], v[134:137], v[196:199], v[76:79]
	v_mfma_f32_16x16x32_bf16 v[76:79], v[138:141], v[200:203], v[76:79]
	v_mfma_f32_16x16x32_bf16 v[72:75], v[142:145], v[196:199], v[72:75]
	v_mfma_f32_16x16x32_bf16 v[72:75], v[146:149], v[200:203], v[72:75]
	v_mfma_f32_16x16x32_bf16 v[88:91], v[142:145], v[182:185], v[88:91]
	v_mfma_f32_16x16x32_bf16 v[88:91], v[146:149], v[192:195], v[88:91]
	v_mfma_f32_16x16x32_bf16 v[104:107], v[142:145], v[174:177], v[104:107]
	v_mfma_f32_16x16x32_bf16 v[104:107], v[146:149], v[178:181], v[104:107]
	v_mfma_f32_16x16x32_bf16 v[120:123], v[142:145], v[166:169], v[120:123]
	v_mfma_f32_16x16x32_bf16 v[120:123], v[146:149], v[170:173], v[120:123]
	s_setprio 0
	s_setprio 1
	s_waitcnt lgkmcnt(0)
	v_mfma_f32_16x16x32_bf16 v[116:119], v[150:153], v[166:169], v[116:119]
	v_mfma_f32_16x16x32_bf16 v[116:119], v[154:157], v[170:173], v[116:119]
	v_mfma_f32_16x16x32_bf16 v[100:103], v[150:153], v[174:177], v[100:103]
	v_mfma_f32_16x16x32_bf16 v[100:103], v[154:157], v[178:181], v[100:103]
	v_mfma_f32_16x16x32_bf16 v[84:87], v[150:153], v[182:185], v[84:87]
	v_mfma_f32_16x16x32_bf16 v[84:87], v[154:157], v[192:195], v[84:87]
	v_mfma_f32_16x16x32_bf16 v[68:71], v[150:153], v[196:199], v[68:71]
	v_mfma_f32_16x16x32_bf16 v[68:71], v[154:157], v[200:203], v[68:71]
	v_mfma_f32_16x16x32_bf16 v[64:67], v[158:161], v[196:199], v[64:67]
	v_mfma_f32_16x16x32_bf16 v[64:67], v[162:165], v[200:203], v[64:67]
	v_mfma_f32_16x16x32_bf16 v[80:83], v[158:161], v[182:185], v[80:83]
	v_mfma_f32_16x16x32_bf16 v[80:83], v[162:165], v[192:195], v[80:83]
	v_mfma_f32_16x16x32_bf16 v[96:99], v[158:161], v[174:177], v[96:99]
	v_mfma_f32_16x16x32_bf16 v[96:99], v[162:165], v[178:181], v[96:99]
	v_mfma_f32_16x16x32_bf16 v[112:115], v[158:161], v[166:169], v[112:115]
	s_barrier
	v_mfma_f32_16x16x32_bf16 v[112:115], v[162:165], v[170:173], v[112:115]
	s_setprio 0
	s_add_u32 s28, s42, 0x2000
	ds_read_b128 v[166:169], v130 offset:16384
	ds_read_b128 v[170:173], v130 offset:17408
	ds_read_b128 v[174:177], v130 offset:18432
	ds_read_b128 v[178:181], v130 offset:19456
	ds_read_b128 v[182:185], v130 offset:20480
	ds_read_b128 v[192:195], v130 offset:21504
	ds_read_b128 v[196:199], v130 offset:22528
	ds_read_b128 v[200:203], v130 offset:23552
	s_mov_b32 m0, s46
	s_nop 0
	global_load_lds_dwordx4 v210, s[42:43]
	s_addc_u32 s29, s43, 0
	s_mov_b32 m0, s47
	s_nop 0
	global_load_lds_dwordx4 v210, s[28:29]
	s_add_u32 s28, s42, 0x4000
	s_addc_u32 s29, s43, 0
	s_mov_b32 m0, s48
	s_nop 0
	global_load_lds_dwordx4 v210, s[28:29]
	s_add_u32 s28, s42, 0x6000
	s_addc_u32 s29, s43, 0
	s_mov_b32 m0, s49
	s_nop 0
	global_load_lds_dwordx4 v210, s[28:29]
	s_add_u32 s28, s38, 0x2000
	s_mov_b32 m0, s45
	s_nop 0
	global_load_lds_dwordx4 v210, s[38:39]
	s_addc_u32 s29, s39, 0
	s_mov_b32 m0, s50
	s_nop 0
	global_load_lds_dwordx4 v210, s[28:29]
	s_waitcnt vmcnt(8)
	s_waitcnt lgkmcnt(0)
	s_barrier
	s_setprio 1
	s_waitcnt lgkmcnt(7)
	s_waitcnt lgkmcnt(0)
	v_mfma_f32_16x16x32_bf16 v[60:63], v[134:137], v[166:169], v[60:63]
	v_mfma_f32_16x16x32_bf16 v[60:63], v[138:141], v[170:173], v[60:63]
	v_mfma_f32_16x16x32_bf16 v[44:47], v[134:137], v[174:177], v[44:47]
	v_mfma_f32_16x16x32_bf16 v[44:47], v[138:141], v[178:181], v[44:47]
	v_mfma_f32_16x16x32_bf16 v[28:31], v[134:137], v[182:185], v[28:31]
	v_mfma_f32_16x16x32_bf16 v[28:31], v[138:141], v[192:195], v[28:31]
	v_mfma_f32_16x16x32_bf16 v[12:15], v[134:137], v[196:199], v[12:15]
	v_mfma_f32_16x16x32_bf16 v[12:15], v[138:141], v[200:203], v[12:15]
	v_mfma_f32_16x16x32_bf16 v[8:11], v[142:145], v[196:199], v[8:11]
	v_mfma_f32_16x16x32_bf16 v[8:11], v[146:149], v[200:203], v[8:11]
	v_mfma_f32_16x16x32_bf16 v[24:27], v[142:145], v[182:185], v[24:27]
	v_mfma_f32_16x16x32_bf16 v[24:27], v[146:149], v[192:195], v[24:27]
	v_mfma_f32_16x16x32_bf16 v[40:43], v[142:145], v[174:177], v[40:43]
	v_mfma_f32_16x16x32_bf16 v[40:43], v[146:149], v[178:181], v[40:43]
	v_mfma_f32_16x16x32_bf16 v[56:59], v[142:145], v[166:169], v[56:59]
	v_mfma_f32_16x16x32_bf16 v[56:59], v[146:149], v[170:173], v[56:59]
	s_setprio 0
	s_setprio 1
	s_waitcnt lgkmcnt(0)
	v_mfma_f32_16x16x32_bf16 v[52:55], v[150:153], v[166:169], v[52:55]
	v_mfma_f32_16x16x32_bf16 v[52:55], v[154:157], v[170:173], v[52:55]
	v_mfma_f32_16x16x32_bf16 v[36:39], v[150:153], v[174:177], v[36:39]
	v_mfma_f32_16x16x32_bf16 v[36:39], v[154:157], v[178:181], v[36:39]
	v_mfma_f32_16x16x32_bf16 v[20:23], v[150:153], v[182:185], v[20:23]
	v_mfma_f32_16x16x32_bf16 v[20:23], v[154:157], v[192:195], v[20:23]
	v_mfma_f32_16x16x32_bf16 v[4:7], v[150:153], v[196:199], v[4:7]
	v_mfma_f32_16x16x32_bf16 v[4:7], v[154:157], v[200:203], v[4:7]
	v_mfma_f32_16x16x32_bf16 v[0:3], v[158:161], v[196:199], v[0:3]
	v_mfma_f32_16x16x32_bf16 v[0:3], v[162:165], v[200:203], v[0:3]
	v_mfma_f32_16x16x32_bf16 v[16:19], v[158:161], v[182:185], v[16:19]
	v_mfma_f32_16x16x32_bf16 v[16:19], v[162:165], v[192:195], v[16:19]
	v_mfma_f32_16x16x32_bf16 v[32:35], v[158:161], v[174:177], v[32:35]
	v_mfma_f32_16x16x32_bf16 v[32:35], v[162:165], v[178:181], v[32:35]
	v_mfma_f32_16x16x32_bf16 v[48:51], v[158:161], v[166:169], v[48:51]
	s_barrier
	v_mfma_f32_16x16x32_bf16 v[48:51], v[162:165], v[170:173], v[48:51]
	s_setprio 0
	ds_read_b128 v[134:137], v131
	ds_read_b128 v[138:141], v131 offset:1024
	ds_read_b128 v[142:145], v131 offset:2048
	ds_read_b128 v[146:149], v131 offset:3072
	ds_read_b128 v[150:153], v132
	ds_read_b128 v[154:157], v132 offset:1024
	ds_read_b128 v[158:161], v132 offset:2048
	ds_read_b128 v[162:165], v132 offset:3072
	ds_read_b128 v[166:169], v130 offset:32768
	ds_read_b128 v[170:173], v130 offset:33792
	ds_read_b128 v[174:177], v130 offset:34816
	ds_read_b128 v[178:181], v130 offset:35840
	ds_read_b128 v[182:185], v130 offset:36864
	ds_read_b128 v[192:195], v130 offset:37888
	ds_read_b128 v[196:199], v130 offset:38912
	ds_read_b128 v[200:203], v130 offset:39936
	s_add_u32 s28, s38, 0x4000
	s_addc_u32 s29, s39, 0
	s_mov_b32 m0, s51
	s_nop 0
	global_load_lds_dwordx4 v210, s[28:29]
	s_add_u32 s28, s38, 0x6000
	s_addc_u32 s29, s39, 0
	s_mov_b32 m0, s52
	s_nop 0
	global_load_lds_dwordx4 v210, s[28:29]
	s_waitcnt vmcnt(8)
	s_waitcnt lgkmcnt(0)
	s_barrier
	s_setprio 1
	s_waitcnt lgkmcnt(7)
	s_waitcnt lgkmcnt(0)
	v_mfma_f32_16x16x32_bf16 v[124:127], v[134:137], v[166:169], v[124:127]
	v_mfma_f32_16x16x32_bf16 v[124:127], v[138:141], v[170:173], v[124:127]
	v_mfma_f32_16x16x32_bf16 v[108:111], v[134:137], v[174:177], v[108:111]
	v_mfma_f32_16x16x32_bf16 v[108:111], v[138:141], v[178:181], v[108:111]
	v_mfma_f32_16x16x32_bf16 v[92:95], v[134:137], v[182:185], v[92:95]
	v_mfma_f32_16x16x32_bf16 v[92:95], v[138:141], v[192:195], v[92:95]
	v_mfma_f32_16x16x32_bf16 v[76:79], v[134:137], v[196:199], v[76:79]
	v_mfma_f32_16x16x32_bf16 v[76:79], v[138:141], v[200:203], v[76:79]
	v_mfma_f32_16x16x32_bf16 v[72:75], v[142:145], v[196:199], v[72:75]
	v_mfma_f32_16x16x32_bf16 v[72:75], v[146:149], v[200:203], v[72:75]
	v_mfma_f32_16x16x32_bf16 v[88:91], v[142:145], v[182:185], v[88:91]
	v_mfma_f32_16x16x32_bf16 v[88:91], v[146:149], v[192:195], v[88:91]
	v_mfma_f32_16x16x32_bf16 v[104:107], v[142:145], v[174:177], v[104:107]
	v_mfma_f32_16x16x32_bf16 v[104:107], v[146:149], v[178:181], v[104:107]
	v_mfma_f32_16x16x32_bf16 v[120:123], v[142:145], v[166:169], v[120:123]
	v_mfma_f32_16x16x32_bf16 v[120:123], v[146:149], v[170:173], v[120:123]
	s_setprio 0
	s_setprio 1
	s_waitcnt lgkmcnt(0)
	v_mfma_f32_16x16x32_bf16 v[116:119], v[150:153], v[166:169], v[116:119]
	v_mfma_f32_16x16x32_bf16 v[116:119], v[154:157], v[170:173], v[116:119]
	v_mfma_f32_16x16x32_bf16 v[100:103], v[150:153], v[174:177], v[100:103]
	v_mfma_f32_16x16x32_bf16 v[100:103], v[154:157], v[178:181], v[100:103]
	v_mfma_f32_16x16x32_bf16 v[84:87], v[150:153], v[182:185], v[84:87]
	v_mfma_f32_16x16x32_bf16 v[84:87], v[154:157], v[192:195], v[84:87]
	v_mfma_f32_16x16x32_bf16 v[68:71], v[150:153], v[196:199], v[68:71]
	v_mfma_f32_16x16x32_bf16 v[68:71], v[154:157], v[200:203], v[68:71]
	v_mfma_f32_16x16x32_bf16 v[64:67], v[158:161], v[196:199], v[64:67]
	v_mfma_f32_16x16x32_bf16 v[64:67], v[162:165], v[200:203], v[64:67]
	v_mfma_f32_16x16x32_bf16 v[80:83], v[158:161], v[182:185], v[80:83]
	v_mfma_f32_16x16x32_bf16 v[80:83], v[162:165], v[192:195], v[80:83]
	v_mfma_f32_16x16x32_bf16 v[96:99], v[158:161], v[174:177], v[96:99]
	v_mfma_f32_16x16x32_bf16 v[96:99], v[162:165], v[178:181], v[96:99]
	v_mfma_f32_16x16x32_bf16 v[112:115], v[158:161], v[166:169], v[112:115]
	s_barrier
	v_mfma_f32_16x16x32_bf16 v[112:115], v[162:165], v[170:173], v[112:115]
	s_setprio 0
	s_add_u32 s28, s42, 0x8000
	s_addc_u32 s29, s43, 0
	ds_read_b128 v[166:169], v130 offset:49152
	ds_read_b128 v[170:173], v130 offset:50176
	ds_read_b128 v[174:177], v130 offset:51200
	ds_read_b128 v[178:181], v130 offset:52224
	ds_read_b128 v[182:185], v130 offset:53248
	ds_read_b128 v[192:195], v130 offset:54272
	ds_read_b128 v[196:199], v130 offset:55296
	ds_read_b128 v[200:203], v130 offset:56320
	s_mov_b32 m0, s53
	s_nop 0
	global_load_lds_dwordx4 v210, s[28:29]
	s_add_u32 s28, s42, 0xa000
	s_addc_u32 s29, s43, 0
	s_mov_b32 m0, s54
	s_nop 0
	global_load_lds_dwordx4 v210, s[28:29]
	s_add_u32 s28, s42, 0xc000
	s_addc_u32 s29, s43, 0
	s_mov_b32 m0, s57
	s_nop 0
	global_load_lds_dwordx4 v210, s[28:29]
	s_add_u32 s28, s42, 0xe000
	s_addc_u32 s29, s43, 0
	s_mov_b32 m0, s58
	s_nop 0
	global_load_lds_dwordx4 v210, s[28:29]
	s_add_u32 s28, s38, 0xa000
	s_mov_b32 m0, s55
	s_nop 0
	global_load_lds_dwordx4 v210, s[40:41]
	s_addc_u32 s29, s39, 0
	s_mov_b32 m0, s56
	s_nop 0
	global_load_lds_dwordx4 v210, s[28:29]
	s_waitcnt vmcnt(8)
	s_waitcnt lgkmcnt(0)
	s_barrier
	s_setprio 1
	s_waitcnt lgkmcnt(7)
	s_waitcnt lgkmcnt(0)
	v_mfma_f32_16x16x32_bf16 v[60:63], v[134:137], v[166:169], v[60:63]
	v_mfma_f32_16x16x32_bf16 v[60:63], v[138:141], v[170:173], v[60:63]
	v_mfma_f32_16x16x32_bf16 v[44:47], v[134:137], v[174:177], v[44:47]
	v_mfma_f32_16x16x32_bf16 v[44:47], v[138:141], v[178:181], v[44:47]
	v_mfma_f32_16x16x32_bf16 v[28:31], v[134:137], v[182:185], v[28:31]
	v_mfma_f32_16x16x32_bf16 v[28:31], v[138:141], v[192:195], v[28:31]
	v_mfma_f32_16x16x32_bf16 v[12:15], v[134:137], v[196:199], v[12:15]
	v_mfma_f32_16x16x32_bf16 v[12:15], v[138:141], v[200:203], v[12:15]
	v_mfma_f32_16x16x32_bf16 v[8:11], v[142:145], v[196:199], v[8:11]
	v_mfma_f32_16x16x32_bf16 v[8:11], v[146:149], v[200:203], v[8:11]
	v_mfma_f32_16x16x32_bf16 v[24:27], v[142:145], v[182:185], v[24:27]
	v_mfma_f32_16x16x32_bf16 v[24:27], v[146:149], v[192:195], v[24:27]
	v_mfma_f32_16x16x32_bf16 v[40:43], v[142:145], v[174:177], v[40:43]
	v_mfma_f32_16x16x32_bf16 v[40:43], v[146:149], v[178:181], v[40:43]
	v_mfma_f32_16x16x32_bf16 v[56:59], v[142:145], v[166:169], v[56:59]
	v_mfma_f32_16x16x32_bf16 v[56:59], v[146:149], v[170:173], v[56:59]
	s_setprio 0
	s_setprio 1
	s_waitcnt lgkmcnt(0)
	v_mfma_f32_16x16x32_bf16 v[52:55], v[150:153], v[166:169], v[52:55]
	v_mfma_f32_16x16x32_bf16 v[52:55], v[154:157], v[170:173], v[52:55]
	v_mfma_f32_16x16x32_bf16 v[36:39], v[150:153], v[174:177], v[36:39]
	v_mfma_f32_16x16x32_bf16 v[36:39], v[154:157], v[178:181], v[36:39]
	v_mfma_f32_16x16x32_bf16 v[20:23], v[150:153], v[182:185], v[20:23]
	v_mfma_f32_16x16x32_bf16 v[20:23], v[154:157], v[192:195], v[20:23]
	v_mfma_f32_16x16x32_bf16 v[4:7], v[150:153], v[196:199], v[4:7]
	v_mfma_f32_16x16x32_bf16 v[4:7], v[154:157], v[200:203], v[4:7]
	v_mfma_f32_16x16x32_bf16 v[0:3], v[158:161], v[196:199], v[0:3]
	v_mfma_f32_16x16x32_bf16 v[0:3], v[162:165], v[200:203], v[0:3]
	v_mfma_f32_16x16x32_bf16 v[16:19], v[158:161], v[182:185], v[16:19]
	v_mfma_f32_16x16x32_bf16 v[16:19], v[162:165], v[192:195], v[16:19]
	v_mfma_f32_16x16x32_bf16 v[32:35], v[158:161], v[174:177], v[32:35]
	v_mfma_f32_16x16x32_bf16 v[32:35], v[162:165], v[178:181], v[32:35]
	v_mfma_f32_16x16x32_bf16 v[48:51], v[158:161], v[166:169], v[48:51]
	s_barrier
	v_mfma_f32_16x16x32_bf16 v[48:51], v[162:165], v[170:173], v[48:51]
	s_setprio 0
	s_nop 7
	s_add_i32 s77, s77, 2
	s_add_u32 s75, s75, 0x10000
	s_addc_u32 s76, s76, 0
	s_cmp_gt_u32 s77, 9
	s_mov_b64 s[28:29], s[2:3]
	s_cbranch_scc0 .LBB0_1953
	v_mbcnt_lo_u32_b32 v128, -1, 0
	v_mbcnt_hi_u32_b32 v128, -1, v128
	s_add_u32 s19, s69, s19
	v_lshlrev_b32_e32 v128, 4, v128
	v_add_u32_e32 v129, s60, v128
	v_add_u32_e32 v128, s62, v128
	s_addc_u32 s17, s70, s17
	s_mov_b32 s23, -2
	v_add_u32_e32 v128, 0, v128
	v_add_u32_e32 v129, 0, v129
	.p2align	6
